# streaming K pass: per-token counted vmcnt waits, log-forget dword issued first
# baseline (speedup 1.0000x reference)
.LBB0_1116:
	s_add_i32 s80, s51, -3
	s_add_i32 s55, s51, 29
	s_cmp_gt_i32 s51, 2
	s_cselect_b64 s[76:77], -1, 0
	s_and_b64 s[38:39], s[76:77], exec
	s_cselect_b32 s82, s11, s1
	s_cselect_b32 s55, s80, s55
	s_cmp_lg_u32 s50, 0
	s_cselect_b64 s[38:39], -1, 0
	s_cmp_eq_u32 s50, 0
	s_cselect_b64 s[74:75], -1, 0
	s_and_b64 s[76:77], s[76:77], s[38:39]
	s_and_b64 s[76:77], s[76:77], exec
	s_cselect_b32 s81, s63, s61
	s_cselect_b32 s84, s62, s60
	s_ashr_i32 s83, s82, 31
	s_lshl_b64 s[76:77], s[82:83], 18
	s_add_u32 s76, s84, s76
	s_addc_u32 s77, s81, s77
	s_lshl_b64 s[82:83], s[82:83], 12
	s_add_u32 s82, s64, s82
	s_addc_u32 s83, s65, s83
	v_lshl_or_b32 v162, s55, 7, v239
	global_load_dword v162, v162, s[82:83] offset:0
	v_lshl_or_b32 v130, s55, 13, v243
	global_load_dwordx4 v[150:153], v130, s[76:77] offset:2048 sc1 nt
	global_load_dwordx4 v[138:141], v130, s[76:77] offset:2176 sc1 nt
	global_load_dwordx4 v[154:157], v130, s[76:77] offset:0 sc1 nt
	global_load_dwordx4 v[142:145], v130, s[76:77] offset:128 sc1 nt
	global_load_dwordx4 v[158:161], v130, s[76:77] offset:-2048 sc1 nt
	global_load_dwordx4 v[146:149], v130, s[76:77] offset:-1920 sc1 nt
	global_load_dwordx4 v[134:137], v130, s[76:77] offset:-4096 sc1 nt
	global_load_dwordx4 v[130:133], v130, s[76:77] offset:-3968 sc1 nt
	s_waitcnt vmcnt(33)
	s_mov_b64 s[76:77], -1
	s_and_b64 vcc, exec, s[74:75]
	s_cbranch_vccz .LBB0_1120
	v_pk_mul_f32 v[164:165], v[18:19], v[94:95]
	v_pk_mul_f32 v[166:167], v[18:19], v[86:87]
	v_pk_mul_f32 v[168:169], v[18:19], v[98:99]
	v_pk_mul_f32 v[170:171], v[18:19], v[110:111]
	v_pk_fma_f32 v[164:165], v[96:97], v[20:21], v[164:165]
	v_pk_fma_f32 v[166:167], v[88:89], v[20:21], v[166:167]
	v_pk_fma_f32 v[168:169], v[100:101], v[20:21], v[168:169]
	v_pk_fma_f32 v[170:171], v[112:113], v[20:21], v[170:171]
	v_pk_fma_f32 v[164:165], v[42:43], v[2:3], v[164:165]
	v_pk_fma_f32 v[166:167], v[58:59], v[2:3], v[166:167]
	v_pk_fma_f32 v[168:169], v[62:63], v[2:3], v[168:169]
	v_pk_fma_f32 v[170:171], v[82:83], v[2:3], v[170:171]
	v_pk_fma_f32 v[164:165], v[44:45], v[4:5], v[164:165]
	v_pk_fma_f32 v[166:167], v[60:61], v[4:5], v[166:167]
	v_pk_fma_f32 v[168:169], v[64:65], v[4:5], v[168:169]
	v_pk_fma_f32 v[170:171], v[84:85], v[4:5], v[170:171]
	v_pk_add_f32 v[164:165], v[164:165], v[164:165] op_sel:[0,1] op_sel_hi:[1,0]
	v_pk_add_f32 v[166:167], v[166:167], v[166:167] op_sel:[0,1] op_sel_hi:[1,0]
	v_pk_add_f32 v[168:169], v[168:169], v[168:169] op_sel:[0,1] op_sel_hi:[1,0]
	v_pk_add_f32 v[170:171], v[170:171], v[170:171] op_sel:[0,1] op_sel_hi:[1,0]
	v_cndmask_b32_e64 v163, v164, v168, s[4:5]
	v_cndmask_b32_e64 v165, v166, v170, s[4:5]
	v_cndmask_b32_e64 v164, v168, v164, s[4:5]
	v_cndmask_b32_e64 v166, v170, v166, s[4:5]
	s_waitcnt vmcnt(31)
	v_pk_mul_f32 v[168:169], v[22:23], v[98:99]
	v_add_f32_dpp v163, v163, v164 quad_perm:[1,0,3,2] row_mask:0xf bank_mask:0xf bound_ctrl:1
	v_add_f32_dpp v164, v165, v166 quad_perm:[1,0,3,2] row_mask:0xf bank_mask:0xf bound_ctrl:1
	v_cndmask_b32_e64 v165, v163, v164, s[6:7]
	v_cndmask_b32_e64 v163, v164, v163, s[6:7]
	v_pk_mul_f32 v[166:167], v[22:23], v[86:87]
	v_pk_mul_f32 v[170:171], v[22:23], v[110:111]
	v_add_f32_dpp v163, v165, v163 quad_perm:[2,3,0,1] row_mask:0xf bank_mask:0xf bound_ctrl:1
	v_pk_mul_f32 v[164:165], v[22:23], v[94:95]
	v_pk_fma_f32 v[166:167], v[88:89], v[24:25], v[166:167]
	v_pk_fma_f32 v[164:165], v[96:97], v[24:25], v[164:165]
	v_pk_fma_f32 v[168:169], v[100:101], v[24:25], v[168:169]
	v_pk_fma_f32 v[170:171], v[112:113], v[24:25], v[170:171]
	v_pk_fma_f32 v[164:165], v[42:43], v[6:7], v[164:165]
	v_pk_fma_f32 v[166:167], v[58:59], v[6:7], v[166:167]
	v_pk_fma_f32 v[168:169], v[62:63], v[6:7], v[168:169]
	v_pk_fma_f32 v[170:171], v[82:83], v[6:7], v[170:171]
	v_pk_fma_f32 v[164:165], v[44:45], v[8:9], v[164:165]
	v_pk_fma_f32 v[166:167], v[60:61], v[8:9], v[166:167]
	v_pk_fma_f32 v[168:169], v[64:65], v[8:9], v[168:169]
	v_pk_fma_f32 v[170:171], v[84:85], v[8:9], v[170:171]
	v_pk_add_f32 v[164:165], v[164:165], v[164:165] op_sel:[0,1] op_sel_hi:[1,0]
	v_pk_add_f32 v[166:167], v[166:167], v[166:167] op_sel:[0,1] op_sel_hi:[1,0]
	v_pk_add_f32 v[168:169], v[168:169], v[168:169] op_sel:[0,1] op_sel_hi:[1,0]
	v_pk_add_f32 v[170:171], v[170:171], v[170:171] op_sel:[0,1] op_sel_hi:[1,0]
	v_cndmask_b32_e64 v165, v164, v168, s[4:5]
	v_cndmask_b32_e64 v167, v166, v170, s[4:5]
	v_cndmask_b32_e64 v164, v168, v164, s[4:5]
	v_cndmask_b32_e64 v166, v170, v166, s[4:5]
	ds_swizzle_b32 v173, v163 offset:swizzle(SWAP,4)
	v_add_f32_dpp v164, v165, v164 quad_perm:[1,0,3,2] row_mask:0xf bank_mask:0xf bound_ctrl:1
	v_add_f32_dpp v165, v167, v166 quad_perm:[1,0,3,2] row_mask:0xf bank_mask:0xf bound_ctrl:1
	v_cndmask_b32_e64 v166, v164, v165, s[6:7]
	v_cndmask_b32_e64 v164, v165, v164, s[6:7]
	v_mov_b32_dpp v172, v227 quad_perm:[0,0,0,0] row_mask:0xf bank_mask:0xf bound_ctrl:1
	s_waitcnt lgkmcnt(0)
	v_add_f32_e32 v163, v163, v173
	v_add_f32_dpp v165, v166, v164 quad_perm:[2,3,0,1] row_mask:0xf bank_mask:0xf bound_ctrl:1
	ds_swizzle_b32 v166, v165 offset:swizzle(SWAP,4)
	v_add_f32_e32 v176, v249, v172
	s_waitcnt vmcnt(29)
	v_pk_mul_f32 v[168:169], v[26:27], v[86:87]
	v_pk_mul_f32 v[170:171], v[26:27], v[98:99]
	v_pk_mul_f32 v[172:173], v[26:27], v[110:111]
	s_waitcnt lgkmcnt(0)
	v_add_f32_e32 v165, v165, v166
	v_pk_mul_f32 v[166:167], v[26:27], v[94:95]
	v_pk_fma_f32 v[168:169], v[88:89], v[28:29], v[168:169]
	v_pk_fma_f32 v[166:167], v[96:97], v[28:29], v[166:167]
	v_pk_fma_f32 v[170:171], v[100:101], v[28:29], v[170:171]
	v_pk_fma_f32 v[172:173], v[112:113], v[28:29], v[172:173]
	v_pk_fma_f32 v[166:167], v[42:43], v[10:11], v[166:167]
	v_pk_fma_f32 v[168:169], v[58:59], v[10:11], v[168:169]
	v_pk_fma_f32 v[170:171], v[62:63], v[10:11], v[170:171]
	v_pk_fma_f32 v[172:173], v[82:83], v[10:11], v[172:173]
	v_pk_fma_f32 v[166:167], v[44:45], v[12:13], v[166:167]
	v_pk_fma_f32 v[168:169], v[60:61], v[12:13], v[168:169]
	v_pk_fma_f32 v[170:171], v[64:65], v[12:13], v[170:171]
	v_pk_fma_f32 v[172:173], v[84:85], v[12:13], v[172:173]
	v_pk_add_f32 v[166:167], v[166:167], v[166:167] op_sel:[0,1] op_sel_hi:[1,0]
	v_pk_add_f32 v[168:169], v[168:169], v[168:169] op_sel:[0,1] op_sel_hi:[1,0]
	v_pk_add_f32 v[170:171], v[170:171], v[170:171] op_sel:[0,1] op_sel_hi:[1,0]
	v_pk_add_f32 v[172:173], v[172:173], v[172:173] op_sel:[0,1] op_sel_hi:[1,0]
	v_cndmask_b32_e64 v167, v166, v170, s[4:5]
	v_cndmask_b32_e64 v169, v168, v172, s[4:5]
	v_cndmask_b32_e64 v166, v170, v166, s[4:5]
	v_cndmask_b32_e64 v168, v172, v168, s[4:5]
	s_waitcnt vmcnt(27)
	v_pk_mul_f32 v[170:171], v[30:31], v[98:99]
	v_add_f32_dpp v166, v167, v166 quad_perm:[1,0,3,2] row_mask:0xf bank_mask:0xf bound_ctrl:1
	v_add_f32_dpp v167, v169, v168 quad_perm:[1,0,3,2] row_mask:0xf bank_mask:0xf bound_ctrl:1
	v_cndmask_b32_e64 v168, v166, v167, s[6:7]
	v_cndmask_b32_e64 v166, v167, v166, s[6:7]
	v_pk_mul_f32 v[172:173], v[30:31], v[110:111]
	v_pk_fma_f32 v[170:171], v[100:101], v[32:33], v[170:171]
	v_add_f32_dpp v177, v168, v166 quad_perm:[2,3,0,1] row_mask:0xf bank_mask:0xf bound_ctrl:1
	v_pk_mul_f32 v[166:167], v[30:31], v[94:95]
	v_pk_mul_f32 v[168:169], v[30:31], v[86:87]
	v_pk_fma_f32 v[166:167], v[96:97], v[32:33], v[166:167]
	v_pk_fma_f32 v[168:169], v[88:89], v[32:33], v[168:169]
	v_pk_fma_f32 v[172:173], v[112:113], v[32:33], v[172:173]
	v_pk_fma_f32 v[166:167], v[42:43], v[14:15], v[166:167]
	v_pk_fma_f32 v[168:169], v[58:59], v[14:15], v[168:169]
	v_pk_fma_f32 v[170:171], v[62:63], v[14:15], v[170:171]
	v_pk_fma_f32 v[172:173], v[82:83], v[14:15], v[172:173]
	v_pk_fma_f32 v[166:167], v[44:45], v[16:17], v[166:167]
	v_pk_fma_f32 v[168:169], v[60:61], v[16:17], v[168:169]
	v_pk_fma_f32 v[170:171], v[64:65], v[16:17], v[170:171]
	v_pk_fma_f32 v[172:173], v[84:85], v[16:17], v[172:173]
	v_pk_add_f32 v[166:167], v[166:167], v[166:167] op_sel:[0,1] op_sel_hi:[1,0]
	v_pk_add_f32 v[168:169], v[168:169], v[168:169] op_sel:[0,1] op_sel_hi:[1,0]
	v_pk_add_f32 v[170:171], v[170:171], v[170:171] op_sel:[0,1] op_sel_hi:[1,0]
	v_pk_add_f32 v[172:173], v[172:173], v[172:173] op_sel:[0,1] op_sel_hi:[1,0]
	v_cndmask_b32_e64 v167, v166, v170, s[4:5]
	v_cndmask_b32_e64 v169, v168, v172, s[4:5]
	v_cndmask_b32_e64 v166, v170, v166, s[4:5]
	v_cndmask_b32_e64 v168, v172, v168, s[4:5]
	ds_swizzle_b32 v178, v177 offset:swizzle(SWAP,4)
	v_add_f32_dpp v166, v167, v166 quad_perm:[1,0,3,2] row_mask:0xf bank_mask:0xf bound_ctrl:1
	v_add_f32_dpp v167, v169, v168 quad_perm:[1,0,3,2] row_mask:0xf bank_mask:0xf bound_ctrl:1
	v_cndmask_b32_e64 v168, v166, v167, s[6:7]
	v_cndmask_b32_e64 v166, v167, v166, s[6:7]
	v_mov_b32_dpp v174, v227 quad_perm:[1,1,1,1] row_mask:0xf bank_mask:0xf bound_ctrl:1
	v_mov_b32_dpp v175, v227 quad_perm:[2,2,2,2] row_mask:0xf bank_mask:0xf bound_ctrl:1
	v_add_f32_dpp v167, v168, v166 quad_perm:[2,3,0,1] row_mask:0xf bank_mask:0xf bound_ctrl:1
	ds_swizzle_b32 v169, v167 offset:swizzle(SWAP,4)
	v_add_f32_e32 v168, v176, v174
	s_waitcnt lgkmcnt(1)
	v_add_f32_e32 v166, v177, v178
	v_fmac_f32_e32 v166, 0x3fb8aa3b, v168
	v_add_f32_e32 v168, v168, v175
	s_waitcnt lgkmcnt(0)
	v_add_f32_e32 v167, v167, v169
	v_mov_b32_dpp v164, v227 quad_perm:[3,3,3,3] row_mask:0xf bank_mask:0xf bound_ctrl:1
	v_fmac_f32_e32 v163, 0x3fb8aa3b, v249
	v_fmac_f32_e32 v165, 0x3fb8aa3b, v176
	v_fmac_f32_e32 v167, 0x3fb8aa3b, v168
	s_and_saveexec_b64 s[76:77], s[8:9]
	s_cbranch_execz .LBB0_1119
	v_lshl_add_u32 v169, s51, 9, v241
	ds_write2_b32 v169, v165, v163 offset0:64 offset1:96
	ds_write2_b32 v169, v167, v166 offset1:32

.LBB0_1120:
	s_andn2_b64 vcc, exec, s[76:77]
	v_lshl_add_u32 v163, s51, 9, v241
	s_cbranch_vccnz .LBB0_1122
	s_waitcnt vmcnt(27)
	ds_read2_b32 v[164:165], v163 offset0:64 offset1:96
	ds_read2_b32 v[166:167], v163 offset1:32
	s_waitcnt lgkmcnt(1)
	v_sub_f32_e32 v165, v165, v248
	v_exp_f32_e32 v165, v165
	v_sub_f32_e32 v164, v164, v248
	v_exp_f32_e32 v164, v164
	s_waitcnt lgkmcnt(0)
	v_sub_f32_e32 v167, v167, v248
	v_exp_f32_e32 v167, v167
	v_add_f32_e32 v169, v249, v165
	v_mov_b32_dpp v168, v165 quad_perm:[0,0,0,0] row_mask:0xf bank_mask:0xf bound_ctrl:1
	v_mov_b32_dpp v170, v165 quad_perm:[2,2,2,2] row_mask:0xf bank_mask:0xf bound_ctrl:1
	v_mov_b32_dpp v172, v165 quad_perm:[1,1,1,1] row_mask:0xf bank_mask:0xf bound_ctrl:1
	v_mov_b32_dpp v174, v165 quad_perm:[3,3,3,3] row_mask:0xf bank_mask:0xf bound_ctrl:1
	v_add_f32_e32 v165, v164, v169
	v_mov_b32_dpp v176, v164 quad_perm:[0,0,0,0] row_mask:0xf bank_mask:0xf bound_ctrl:1
	v_mov_b32_dpp v178, v164 quad_perm:[2,2,2,2] row_mask:0xf bank_mask:0xf bound_ctrl:1
	v_mov_b32_dpp v180, v164 quad_perm:[1,1,1,1] row_mask:0xf bank_mask:0xf bound_ctrl:1
	v_mov_b32_dpp v182, v164 quad_perm:[3,3,3,3] row_mask:0xf bank_mask:0xf bound_ctrl:1
	v_add_f32_e32 v164, v167, v165
	v_sub_f32_e32 v165, v166, v248
	v_exp_f32_e32 v165, v165
	v_pk_fma_f32 v[94:95], v[168:169], v[18:19], v[94:95] op_sel_hi:[0,1,1]
	v_pk_fma_f32 v[86:87], v[170:171], v[18:19], v[86:87] op_sel_hi:[0,1,1]
	v_pk_fma_f32 v[98:99], v[172:173], v[18:19], v[98:99] op_sel_hi:[0,1,1]
	v_pk_fma_f32 v[18:19], v[174:175], v[18:19], v[110:111] op_sel_hi:[0,1,1]
	v_mov_b32_dpp v188, v167 quad_perm:[3,3,3,3] row_mask:0xf bank_mask:0xf bound_ctrl:1
	v_pk_fma_f32 v[18:19], v[182:183], v[22:23], v[18:19] op_sel_hi:[0,1,1]
	v_mov_b32_dpp v196, v165 quad_perm:[3,3,3,3] row_mask:0xf bank_mask:0xf bound_ctrl:1
	v_pk_fma_f32 v[18:19], v[188:189], v[26:27], v[18:19] op_sel_hi:[0,1,1]
	v_pk_fma_f32 v[110:111], v[196:197], v[30:31], v[18:19] op_sel_hi:[0,1,1]
	v_pk_fma_f32 v[18:19], v[168:169], v[20:21], v[96:97] op_sel_hi:[0,1,1]
	v_mov_b32_dpp v184, v167 quad_perm:[0,0,0,0] row_mask:0xf bank_mask:0xf bound_ctrl:1
	v_pk_fma_f32 v[18:19], v[176:177], v[24:25], v[18:19] op_sel_hi:[0,1,1]
	v_mov_b32_dpp v190, v165 quad_perm:[0,0,0,0] row_mask:0xf bank_mask:0xf bound_ctrl:1
	v_pk_fma_f32 v[18:19], v[184:185], v[28:29], v[18:19] op_sel_hi:[0,1,1]
	v_pk_fma_f32 v[96:97], v[190:191], v[32:33], v[18:19] op_sel_hi:[0,1,1]
	v_pk_fma_f32 v[18:19], v[170:171], v[20:21], v[88:89] op_sel_hi:[0,1,1]
	v_mov_b32_dpp v166, v167 quad_perm:[2,2,2,2] row_mask:0xf bank_mask:0xf bound_ctrl:1
	v_pk_fma_f32 v[18:19], v[178:179], v[24:25], v[18:19] op_sel_hi:[0,1,1]
	v_mov_b32_dpp v192, v165 quad_perm:[2,2,2,2] row_mask:0xf bank_mask:0xf bound_ctrl:1
	v_pk_fma_f32 v[18:19], v[166:167], v[28:29], v[18:19] op_sel_hi:[0,1,1]
	v_pk_fma_f32 v[88:89], v[192:193], v[32:33], v[18:19] op_sel_hi:[0,1,1]
	v_pk_fma_f32 v[18:19], v[172:173], v[20:21], v[100:101] op_sel_hi:[0,1,1]
	v_mov_b32_dpp v186, v167 quad_perm:[1,1,1,1] row_mask:0xf bank_mask:0xf bound_ctrl:1
	v_pk_fma_f32 v[18:19], v[180:181], v[24:25], v[18:19] op_sel_hi:[0,1,1]
	v_mov_b32_dpp v194, v165 quad_perm:[1,1,1,1] row_mask:0xf bank_mask:0xf bound_ctrl:1
	v_pk_fma_f32 v[18:19], v[186:187], v[28:29], v[18:19] op_sel_hi:[0,1,1]
	v_pk_fma_f32 v[100:101], v[194:195], v[32:33], v[18:19] op_sel_hi:[0,1,1]
	v_pk_fma_f32 v[18:19], v[174:175], v[20:21], v[112:113] op_sel_hi:[0,1,1]
	v_pk_fma_f32 v[18:19], v[182:183], v[24:25], v[18:19] op_sel_hi:[0,1,1]
	v_pk_fma_f32 v[18:19], v[188:189], v[28:29], v[18:19] op_sel_hi:[0,1,1]
	v_pk_fma_f32 v[112:113], v[196:197], v[32:33], v[18:19] op_sel_hi:[0,1,1]
	v_pk_fma_f32 v[18:19], v[168:169], v[2:3], v[42:43] op_sel_hi:[0,1,1]
	v_pk_fma_f32 v[18:19], v[176:177], v[6:7], v[18:19] op_sel_hi:[0,1,1]
	v_pk_fma_f32 v[18:19], v[184:185], v[10:11], v[18:19] op_sel_hi:[0,1,1]
	v_pk_fma_f32 v[42:43], v[190:191], v[14:15], v[18:19] op_sel_hi:[0,1,1]
	v_pk_fma_f32 v[18:19], v[170:171], v[2:3], v[58:59] op_sel_hi:[0,1,1]
	v_pk_fma_f32 v[18:19], v[178:179], v[6:7], v[18:19] op_sel_hi:[0,1,1]
	v_pk_fma_f32 v[18:19], v[166:167], v[10:11], v[18:19] op_sel_hi:[0,1,1]
	v_pk_fma_f32 v[58:59], v[192:193], v[14:15], v[18:19] op_sel_hi:[0,1,1]
	v_pk_fma_f32 v[18:19], v[172:173], v[2:3], v[62:63] op_sel_hi:[0,1,1]
	v_pk_fma_f32 v[2:3], v[174:175], v[2:3], v[82:83] op_sel_hi:[0,1,1]
	v_pk_fma_f32 v[2:3], v[182:183], v[6:7], v[2:3] op_sel_hi:[0,1,1]
	v_pk_fma_f32 v[2:3], v[188:189], v[10:11], v[2:3] op_sel_hi:[0,1,1]
	v_pk_fma_f32 v[82:83], v[196:197], v[14:15], v[2:3] op_sel_hi:[0,1,1]
	v_pk_fma_f32 v[2:3], v[168:169], v[4:5], v[44:45] op_sel_hi:[0,1,1]
	v_pk_fma_f32 v[2:3], v[176:177], v[8:9], v[2:3] op_sel_hi:[0,1,1]
	v_pk_fma_f32 v[2:3], v[184:185], v[12:13], v[2:3] op_sel_hi:[0,1,1]
	v_pk_fma_f32 v[44:45], v[190:191], v[16:17], v[2:3] op_sel_hi:[0,1,1]
	v_pk_fma_f32 v[2:3], v[170:171], v[4:5], v[60:61] op_sel_hi:[0,1,1]
	v_pk_fma_f32 v[2:3], v[178:179], v[8:9], v[2:3] op_sel_hi:[0,1,1]
	v_pk_fma_f32 v[2:3], v[166:167], v[12:13], v[2:3] op_sel_hi:[0,1,1]
	v_pk_fma_f32 v[60:61], v[192:193], v[16:17], v[2:3] op_sel_hi:[0,1,1]
	v_pk_fma_f32 v[2:3], v[172:173], v[4:5], v[64:65] op_sel_hi:[0,1,1]
	v_pk_fma_f32 v[2:3], v[180:181], v[8:9], v[2:3] op_sel_hi:[0,1,1]
	v_pk_fma_f32 v[2:3], v[186:187], v[12:13], v[2:3] op_sel_hi:[0,1,1]
	v_pk_fma_f32 v[64:65], v[194:195], v[16:17], v[2:3] op_sel_hi:[0,1,1]
	v_pk_fma_f32 v[2:3], v[174:175], v[4:5], v[84:85] op_sel_hi:[0,1,1]
	v_pk_fma_f32 v[94:95], v[176:177], v[22:23], v[94:95] op_sel_hi:[0,1,1]
	v_pk_fma_f32 v[86:87], v[178:179], v[22:23], v[86:87] op_sel_hi:[0,1,1]
	v_pk_fma_f32 v[98:99], v[180:181], v[22:23], v[98:99] op_sel_hi:[0,1,1]
	v_pk_fma_f32 v[18:19], v[180:181], v[6:7], v[18:19] op_sel_hi:[0,1,1]
	v_pk_fma_f32 v[2:3], v[182:183], v[8:9], v[2:3] op_sel_hi:[0,1,1]
	v_pk_fma_f32 v[94:95], v[184:185], v[26:27], v[94:95] op_sel_hi:[0,1,1]
	v_pk_fma_f32 v[86:87], v[166:167], v[26:27], v[86:87] op_sel_hi:[0,1,1]
	v_pk_fma_f32 v[98:99], v[186:187], v[26:27], v[98:99] op_sel_hi:[0,1,1]
	v_pk_fma_f32 v[18:19], v[186:187], v[10:11], v[18:19] op_sel_hi:[0,1,1]
	v_pk_fma_f32 v[2:3], v[188:189], v[12:13], v[2:3] op_sel_hi:[0,1,1]
	v_add_f32_e32 v164, v165, v164
	v_pk_fma_f32 v[94:95], v[190:191], v[30:31], v[94:95] op_sel_hi:[0,1,1]
	v_pk_fma_f32 v[86:87], v[192:193], v[30:31], v[86:87] op_sel_hi:[0,1,1]
	v_pk_fma_f32 v[98:99], v[194:195], v[30:31], v[98:99] op_sel_hi:[0,1,1]
	v_pk_fma_f32 v[62:63], v[194:195], v[14:15], v[18:19] op_sel_hi:[0,1,1]
	v_pk_fma_f32 v[84:85], v[196:197], v[16:17], v[2:3] op_sel_hi:[0,1,1]
	s_branch .LBB0_1123

.LBB0_1123:
	s_add_i32 s55, s51, -4
	s_add_i32 s81, s51, 28
	s_cmp_gt_i32 s51, 3
	s_cselect_b64 s[76:77], -1, 0
	s_and_b64 s[82:83], s[76:77], exec
	s_cselect_b32 s82, s11, s1
	s_cselect_b32 s81, s55, s81
	s_and_b64 s[76:77], s[76:77], s[38:39]
	s_and_b64 s[76:77], s[76:77], exec
	s_cselect_b32 s84, s63, s61
	s_cselect_b32 s85, s62, s60
	s_ashr_i32 s83, s82, 31
	s_lshl_b64 s[76:77], s[82:83], 18
	s_add_u32 s76, s85, s76
	s_addc_u32 s77, s84, s77
	s_lshl_b64 s[82:83], s[82:83], 12
	s_add_u32 s82, s64, s82
	s_addc_u32 s83, s65, s83
	v_lshl_or_b32 v165, s81, 7, v239
	global_load_dword v227, v165, s[82:83] offset:0
	v_lshl_or_b32 v14, s81, 13, v243
	global_load_dwordx4 v[18:21], v14, s[76:77] offset:2048 sc1 nt
	global_load_dwordx4 v[2:5], v14, s[76:77] offset:2176 sc1 nt
	global_load_dwordx4 v[22:25], v14, s[76:77] offset:0 sc1 nt
	global_load_dwordx4 v[6:9], v14, s[76:77] offset:128 sc1 nt
	global_load_dwordx4 v[26:29], v14, s[76:77] offset:-2048 sc1 nt
	global_load_dwordx4 v[10:13], v14, s[76:77] offset:-1920 sc1 nt
	global_load_dwordx4 v[30:33], v14, s[76:77] offset:-4096 sc1 nt
	global_load_dwordx4 v[14:17], v14, s[76:77] offset:-3968 sc1 nt
	s_waitcnt vmcnt(33)
	s_mov_b64 s[76:77], -1
	s_and_b64 vcc, exec, s[74:75]
	s_cbranch_vccz .LBB0_1127
	v_pk_mul_f32 v[166:167], v[66:67], v[94:95]
	v_pk_mul_f32 v[168:169], v[66:67], v[86:87]
	v_pk_mul_f32 v[170:171], v[66:67], v[98:99]
	v_pk_mul_f32 v[172:173], v[66:67], v[110:111]
	v_pk_fma_f32 v[166:167], v[96:97], v[68:69], v[166:167]
	v_pk_fma_f32 v[168:169], v[88:89], v[68:69], v[168:169]
	v_pk_fma_f32 v[170:171], v[100:101], v[68:69], v[170:171]
	v_pk_fma_f32 v[172:173], v[112:113], v[68:69], v[172:173]
	v_pk_fma_f32 v[166:167], v[42:43], v[46:47], v[166:167]
	v_pk_fma_f32 v[168:169], v[58:59], v[46:47], v[168:169]
	v_pk_fma_f32 v[170:171], v[62:63], v[46:47], v[170:171]
	v_pk_fma_f32 v[172:173], v[82:83], v[46:47], v[172:173]
	v_pk_fma_f32 v[166:167], v[44:45], v[48:49], v[166:167]
	v_pk_fma_f32 v[168:169], v[60:61], v[48:49], v[168:169]
	v_pk_fma_f32 v[170:171], v[64:65], v[48:49], v[170:171]
	v_pk_fma_f32 v[172:173], v[84:85], v[48:49], v[172:173]
	v_pk_add_f32 v[166:167], v[166:167], v[166:167] op_sel:[0,1] op_sel_hi:[1,0]
	v_pk_add_f32 v[168:169], v[168:169], v[168:169] op_sel:[0,1] op_sel_hi:[1,0]
	v_pk_add_f32 v[170:171], v[170:171], v[170:171] op_sel:[0,1] op_sel_hi:[1,0]
	v_pk_add_f32 v[172:173], v[172:173], v[172:173] op_sel:[0,1] op_sel_hi:[1,0]
	v_cndmask_b32_e64 v165, v166, v170, s[4:5]
	v_cndmask_b32_e64 v167, v168, v172, s[4:5]
	v_cndmask_b32_e64 v166, v170, v166, s[4:5]
	v_cndmask_b32_e64 v168, v172, v168, s[4:5]
	s_waitcnt vmcnt(31)
	v_pk_mul_f32 v[170:171], v[74:75], v[98:99]
	v_add_f32_dpp v165, v165, v166 quad_perm:[1,0,3,2] row_mask:0xf bank_mask:0xf bound_ctrl:1
	v_add_f32_dpp v166, v167, v168 quad_perm:[1,0,3,2] row_mask:0xf bank_mask:0xf bound_ctrl:1
	v_cndmask_b32_e64 v167, v165, v166, s[6:7]
	v_cndmask_b32_e64 v165, v166, v165, s[6:7]
	v_pk_mul_f32 v[168:169], v[74:75], v[86:87]
	v_pk_mul_f32 v[172:173], v[74:75], v[110:111]
	v_add_f32_dpp v175, v167, v165 quad_perm:[2,3,0,1] row_mask:0xf bank_mask:0xf bound_ctrl:1
	v_pk_mul_f32 v[166:167], v[74:75], v[94:95]
	v_pk_fma_f32 v[168:169], v[88:89], v[76:77], v[168:169]
	v_pk_fma_f32 v[166:167], v[96:97], v[76:77], v[166:167]
	v_pk_fma_f32 v[170:171], v[100:101], v[76:77], v[170:171]
	v_pk_fma_f32 v[172:173], v[112:113], v[76:77], v[172:173]
	v_pk_fma_f32 v[166:167], v[42:43], v[50:51], v[166:167]
	v_pk_fma_f32 v[168:169], v[58:59], v[50:51], v[168:169]
	v_pk_fma_f32 v[170:171], v[62:63], v[50:51], v[170:171]
	v_pk_fma_f32 v[172:173], v[82:83], v[50:51], v[172:173]
	v_pk_fma_f32 v[166:167], v[44:45], v[52:53], v[166:167]
	v_pk_fma_f32 v[168:169], v[60:61], v[52:53], v[168:169]
	v_pk_fma_f32 v[170:171], v[64:65], v[52:53], v[170:171]
	v_pk_fma_f32 v[172:173], v[84:85], v[52:53], v[172:173]
	v_pk_add_f32 v[166:167], v[166:167], v[166:167] op_sel:[0,1] op_sel_hi:[1,0]
	v_pk_add_f32 v[168:169], v[168:169], v[168:169] op_sel:[0,1] op_sel_hi:[1,0]
	v_pk_add_f32 v[170:171], v[170:171], v[170:171] op_sel:[0,1] op_sel_hi:[1,0]
	v_pk_add_f32 v[172:173], v[172:173], v[172:173] op_sel:[0,1] op_sel_hi:[1,0]
	v_cndmask_b32_e64 v165, v166, v170, s[4:5]
	v_cndmask_b32_e64 v167, v168, v172, s[4:5]
	v_cndmask_b32_e64 v166, v170, v166, s[4:5]
	v_cndmask_b32_e64 v168, v172, v168, s[4:5]
	ds_swizzle_b32 v178, v175 offset:swizzle(SWAP,4)
	v_add_f32_dpp v165, v165, v166 quad_perm:[1,0,3,2] row_mask:0xf bank_mask:0xf bound_ctrl:1
	v_add_f32_dpp v166, v167, v168 quad_perm:[1,0,3,2] row_mask:0xf bank_mask:0xf bound_ctrl:1
	v_cndmask_b32_e64 v167, v165, v166, s[6:7]
	v_cndmask_b32_e64 v165, v166, v165, s[6:7]
	v_mov_b32_dpp v174, v246 quad_perm:[0,0,0,0] row_mask:0xf bank_mask:0xf bound_ctrl:1
	s_waitcnt lgkmcnt(0)
	v_add_f32_e32 v166, v175, v178
	v_add_f32_dpp v167, v167, v165 quad_perm:[2,3,0,1] row_mask:0xf bank_mask:0xf bound_ctrl:1
	ds_swizzle_b32 v168, v167 offset:swizzle(SWAP,4)
	v_add_f32_e32 v178, v164, v174
	s_waitcnt vmcnt(29)
	v_pk_mul_f32 v[170:171], v[78:79], v[86:87]
	v_pk_mul_f32 v[172:173], v[78:79], v[98:99]
	v_pk_mul_f32 v[174:175], v[78:79], v[110:111]
	s_waitcnt lgkmcnt(0)
	v_add_f32_e32 v167, v167, v168
	v_pk_mul_f32 v[168:169], v[78:79], v[94:95]
	v_pk_fma_f32 v[170:171], v[88:89], v[80:81], v[170:171]
	v_pk_fma_f32 v[168:169], v[96:97], v[80:81], v[168:169]
	v_pk_fma_f32 v[172:173], v[100:101], v[80:81], v[172:173]
	v_pk_fma_f32 v[174:175], v[112:113], v[80:81], v[174:175]
	v_pk_fma_f32 v[168:169], v[42:43], v[54:55], v[168:169]
	v_pk_fma_f32 v[170:171], v[58:59], v[54:55], v[170:171]
	v_pk_fma_f32 v[172:173], v[62:63], v[54:55], v[172:173]
	v_pk_fma_f32 v[174:175], v[82:83], v[54:55], v[174:175]
	v_pk_fma_f32 v[168:169], v[44:45], v[56:57], v[168:169]
	v_pk_fma_f32 v[170:171], v[60:61], v[56:57], v[170:171]
	v_pk_fma_f32 v[172:173], v[64:65], v[56:57], v[172:173]
	v_pk_fma_f32 v[174:175], v[84:85], v[56:57], v[174:175]
	v_pk_add_f32 v[168:169], v[168:169], v[168:169] op_sel:[0,1] op_sel_hi:[1,0]
	v_pk_add_f32 v[170:171], v[170:171], v[170:171] op_sel:[0,1] op_sel_hi:[1,0]
	v_pk_add_f32 v[172:173], v[172:173], v[172:173] op_sel:[0,1] op_sel_hi:[1,0]
	v_pk_add_f32 v[174:175], v[174:175], v[174:175] op_sel:[0,1] op_sel_hi:[1,0]
	v_cndmask_b32_e64 v169, v168, v172, s[4:5]
	v_cndmask_b32_e64 v171, v170, v174, s[4:5]
	v_cndmask_b32_e64 v168, v172, v168, s[4:5]
	v_cndmask_b32_e64 v170, v174, v170, s[4:5]
	s_waitcnt vmcnt(27)
	v_pk_mul_f32 v[172:173], v[38:39], v[98:99]
	v_add_f32_dpp v168, v169, v168 quad_perm:[1,0,3,2] row_mask:0xf bank_mask:0xf bound_ctrl:1
	v_add_f32_dpp v169, v171, v170 quad_perm:[1,0,3,2] row_mask:0xf bank_mask:0xf bound_ctrl:1
	v_cndmask_b32_e64 v170, v168, v169, s[6:7]
	v_cndmask_b32_e64 v168, v169, v168, s[6:7]
	v_pk_mul_f32 v[174:175], v[38:39], v[110:111]
	v_pk_fma_f32 v[172:173], v[100:101], v[40:41], v[172:173]
	v_add_f32_dpp v179, v170, v168 quad_perm:[2,3,0,1] row_mask:0xf bank_mask:0xf bound_ctrl:1
	v_pk_mul_f32 v[168:169], v[38:39], v[94:95]
	v_pk_mul_f32 v[170:171], v[38:39], v[86:87]
	v_pk_fma_f32 v[168:169], v[96:97], v[40:41], v[168:169]
	v_pk_fma_f32 v[170:171], v[88:89], v[40:41], v[170:171]
	v_pk_fma_f32 v[174:175], v[112:113], v[40:41], v[174:175]
	v_pk_fma_f32 v[168:169], v[42:43], v[34:35], v[168:169]
	v_pk_fma_f32 v[170:171], v[58:59], v[34:35], v[170:171]
	v_pk_fma_f32 v[172:173], v[62:63], v[34:35], v[172:173]
	v_pk_fma_f32 v[174:175], v[82:83], v[34:35], v[174:175]
	v_pk_fma_f32 v[168:169], v[44:45], v[36:37], v[168:169]
	v_pk_fma_f32 v[170:171], v[60:61], v[36:37], v[170:171]
	v_pk_fma_f32 v[172:173], v[64:65], v[36:37], v[172:173]
	v_pk_fma_f32 v[174:175], v[84:85], v[36:37], v[174:175]
	v_pk_add_f32 v[168:169], v[168:169], v[168:169] op_sel:[0,1] op_sel_hi:[1,0]
	v_pk_add_f32 v[170:171], v[170:171], v[170:171] op_sel:[0,1] op_sel_hi:[1,0]
	v_pk_add_f32 v[172:173], v[172:173], v[172:173] op_sel:[0,1] op_sel_hi:[1,0]
	v_pk_add_f32 v[174:175], v[174:175], v[174:175] op_sel:[0,1] op_sel_hi:[1,0]
	v_cndmask_b32_e64 v169, v168, v172, s[4:5]
	v_cndmask_b32_e64 v171, v170, v174, s[4:5]
	v_cndmask_b32_e64 v168, v172, v168, s[4:5]
	v_cndmask_b32_e64 v170, v174, v170, s[4:5]
	ds_swizzle_b32 v180, v179 offset:swizzle(SWAP,4)
	v_add_f32_dpp v168, v169, v168 quad_perm:[1,0,3,2] row_mask:0xf bank_mask:0xf bound_ctrl:1
	v_add_f32_dpp v169, v171, v170 quad_perm:[1,0,3,2] row_mask:0xf bank_mask:0xf bound_ctrl:1
	v_cndmask_b32_e64 v170, v168, v169, s[6:7]
	v_cndmask_b32_e64 v168, v169, v168, s[6:7]
	v_mov_b32_dpp v176, v246 quad_perm:[1,1,1,1] row_mask:0xf bank_mask:0xf bound_ctrl:1
	v_mov_b32_dpp v177, v246 quad_perm:[2,2,2,2] row_mask:0xf bank_mask:0xf bound_ctrl:1
	v_add_f32_dpp v169, v170, v168 quad_perm:[2,3,0,1] row_mask:0xf bank_mask:0xf bound_ctrl:1
	ds_swizzle_b32 v171, v169 offset:swizzle(SWAP,4)
	v_add_f32_e32 v170, v178, v176
	s_waitcnt lgkmcnt(1)
	v_add_f32_e32 v168, v179, v180
	v_fmac_f32_e32 v168, 0x3fb8aa3b, v170
	v_add_f32_e32 v170, v170, v177
	s_waitcnt lgkmcnt(0)
	v_add_f32_e32 v169, v169, v171
	v_mov_b32_dpp v165, v246 quad_perm:[3,3,3,3] row_mask:0xf bank_mask:0xf bound_ctrl:1
	v_fmac_f32_e32 v166, 0x3fb8aa3b, v164
	v_fmac_f32_e32 v167, 0x3fb8aa3b, v178
	v_fmac_f32_e32 v169, 0x3fb8aa3b, v170
	s_and_saveexec_b64 s[76:77], s[8:9]
	s_cbranch_execz .LBB0_1126
	v_add_u32_e32 v173, 0xffffff80, v163
	v_add_u32_e32 v171, 0xfffffe80, v163
	v_add_u32_e32 v172, 0xffffff00, v163
	v_add_u32_e32 v174, 0xfffffe00, v163
	ds_write_b32 v173, v166
	ds_write_b32 v172, v167
	ds_write_b32 v171, v168
	ds_write_b32 v174, v169

.LBB0_1127:
	s_andn2_b64 vcc, exec, s[76:77]
	s_cbranch_vccnz .LBB0_1129
	s_waitcnt vmcnt(27)
	v_add_u32_e32 v166, 0xffffff80, v163
	ds_read_b32 v166, v166
	v_add_u32_e32 v165, 0xfffffe00, v163
	v_add_u32_e32 v167, 0xffffff00, v163
	v_add_u32_e32 v168, 0xfffffe80, v163
	ds_read_b32 v167, v167
	ds_read_b32 v169, v168
	ds_read_b32 v165, v165
	s_waitcnt lgkmcnt(3)
	v_sub_f32_e32 v166, v166, v248
	v_exp_f32_e32 v170, v166
	s_waitcnt lgkmcnt(2)
	v_sub_f32_e32 v166, v167, v248
	v_exp_f32_e32 v167, v166
	s_waitcnt lgkmcnt(1)
	v_sub_f32_e32 v169, v169, v248
	v_exp_f32_e32 v169, v169
	v_add_f32_e32 v171, v164, v170
	v_add_f32_e32 v171, v167, v171
	v_mov_b32_dpp v164, v170 quad_perm:[0,0,0,0] row_mask:0xf bank_mask:0xf bound_ctrl:1
	v_mov_b32_dpp v166, v170 quad_perm:[2,2,2,2] row_mask:0xf bank_mask:0xf bound_ctrl:1
	v_mov_b32_dpp v168, v170 quad_perm:[1,1,1,1] row_mask:0xf bank_mask:0xf bound_ctrl:1
	v_mov_b32_dpp v170, v170 quad_perm:[3,3,3,3] row_mask:0xf bank_mask:0xf bound_ctrl:1
	v_mov_b32_dpp v172, v167 quad_perm:[0,0,0,0] row_mask:0xf bank_mask:0xf bound_ctrl:1
	v_mov_b32_dpp v174, v167 quad_perm:[2,2,2,2] row_mask:0xf bank_mask:0xf bound_ctrl:1
	v_mov_b32_dpp v176, v167 quad_perm:[1,1,1,1] row_mask:0xf bank_mask:0xf bound_ctrl:1
	v_mov_b32_dpp v178, v167 quad_perm:[3,3,3,3] row_mask:0xf bank_mask:0xf bound_ctrl:1
	v_add_f32_e32 v167, v169, v171
	s_waitcnt lgkmcnt(0)
	v_pk_fma_f32 v[42:43], v[164:165], v[46:47], v[42:43] op_sel_hi:[0,1,1]
	v_pk_fma_f32 v[58:59], v[166:167], v[46:47], v[58:59] op_sel_hi:[0,1,1]
	v_pk_fma_f32 v[62:63], v[168:169], v[46:47], v[62:63] op_sel_hi:[0,1,1]
	v_pk_fma_f32 v[46:47], v[170:171], v[46:47], v[82:83] op_sel_hi:[0,1,1]
	v_pk_fma_f32 v[42:43], v[172:173], v[50:51], v[42:43] op_sel_hi:[0,1,1]
	v_pk_fma_f32 v[58:59], v[174:175], v[50:51], v[58:59] op_sel_hi:[0,1,1]
	v_pk_fma_f32 v[62:63], v[176:177], v[50:51], v[62:63] op_sel_hi:[0,1,1]
	v_pk_fma_f32 v[46:47], v[178:179], v[50:51], v[46:47] op_sel_hi:[0,1,1]
	v_pk_fma_f32 v[50:51], v[166:167], v[48:49], v[60:61] op_sel_hi:[0,1,1]
	v_sub_f32_e32 v60, v165, v248
	v_pk_fma_f32 v[94:95], v[164:165], v[66:67], v[94:95] op_sel_hi:[0,1,1]
	v_pk_fma_f32 v[86:87], v[166:167], v[66:67], v[86:87] op_sel_hi:[0,1,1]
	v_pk_fma_f32 v[98:99], v[168:169], v[66:67], v[98:99] op_sel_hi:[0,1,1]
	v_pk_fma_f32 v[66:67], v[170:171], v[66:67], v[110:111] op_sel_hi:[0,1,1]
	v_exp_f32_e32 v60, v60
	v_mov_b32_dpp v180, v169 quad_perm:[0,0,0,0] row_mask:0xf bank_mask:0xf bound_ctrl:1
	v_mov_b32_dpp v182, v169 quad_perm:[2,2,2,2] row_mask:0xf bank_mask:0xf bound_ctrl:1
	v_mov_b32_dpp v184, v169 quad_perm:[1,1,1,1] row_mask:0xf bank_mask:0xf bound_ctrl:1
	v_mov_b32_dpp v186, v169 quad_perm:[3,3,3,3] row_mask:0xf bank_mask:0xf bound_ctrl:1
	v_pk_fma_f32 v[94:95], v[172:173], v[74:75], v[94:95] op_sel_hi:[0,1,1]
	v_pk_fma_f32 v[86:87], v[174:175], v[74:75], v[86:87] op_sel_hi:[0,1,1]
	v_pk_fma_f32 v[98:99], v[176:177], v[74:75], v[98:99] op_sel_hi:[0,1,1]
	v_pk_fma_f32 v[66:67], v[178:179], v[74:75], v[66:67] op_sel_hi:[0,1,1]
	v_pk_fma_f32 v[94:95], v[180:181], v[78:79], v[94:95] op_sel_hi:[0,1,1]
	v_pk_fma_f32 v[86:87], v[182:183], v[78:79], v[86:87] op_sel_hi:[0,1,1]
	v_pk_fma_f32 v[98:99], v[184:185], v[78:79], v[98:99] op_sel_hi:[0,1,1]
	v_pk_fma_f32 v[66:67], v[186:187], v[78:79], v[66:67] op_sel_hi:[0,1,1]
	v_pk_fma_f32 v[74:75], v[164:165], v[68:69], v[96:97] op_sel_hi:[0,1,1]
	v_pk_fma_f32 v[78:79], v[166:167], v[68:69], v[88:89] op_sel_hi:[0,1,1]
	v_pk_fma_f32 v[88:89], v[168:169], v[68:69], v[100:101] op_sel_hi:[0,1,1]
	v_pk_fma_f32 v[68:69], v[170:171], v[68:69], v[112:113] op_sel_hi:[0,1,1]
	v_pk_fma_f32 v[42:43], v[180:181], v[54:55], v[42:43] op_sel_hi:[0,1,1]
	v_pk_fma_f32 v[58:59], v[182:183], v[54:55], v[58:59] op_sel_hi:[0,1,1]
	v_pk_fma_f32 v[62:63], v[184:185], v[54:55], v[62:63] op_sel_hi:[0,1,1]
	v_pk_fma_f32 v[46:47], v[186:187], v[54:55], v[46:47] op_sel_hi:[0,1,1]
	v_pk_fma_f32 v[44:45], v[164:165], v[48:49], v[44:45] op_sel_hi:[0,1,1]
	v_pk_fma_f32 v[54:55], v[168:169], v[48:49], v[64:65] op_sel_hi:[0,1,1]
	v_pk_fma_f32 v[48:49], v[170:171], v[48:49], v[84:85] op_sel_hi:[0,1,1]
	v_pk_fma_f32 v[74:75], v[172:173], v[76:77], v[74:75] op_sel_hi:[0,1,1]
	v_pk_fma_f32 v[78:79], v[174:175], v[76:77], v[78:79] op_sel_hi:[0,1,1]
	v_pk_fma_f32 v[88:89], v[176:177], v[76:77], v[88:89] op_sel_hi:[0,1,1]
	v_pk_fma_f32 v[68:69], v[178:179], v[76:77], v[68:69] op_sel_hi:[0,1,1]
	v_pk_fma_f32 v[44:45], v[172:173], v[52:53], v[44:45] op_sel_hi:[0,1,1]
	v_pk_fma_f32 v[50:51], v[174:175], v[52:53], v[50:51] op_sel_hi:[0,1,1]
	v_pk_fma_f32 v[54:55], v[176:177], v[52:53], v[54:55] op_sel_hi:[0,1,1]
	v_pk_fma_f32 v[48:49], v[178:179], v[52:53], v[48:49] op_sel_hi:[0,1,1]
	v_pk_fma_f32 v[74:75], v[180:181], v[80:81], v[74:75] op_sel_hi:[0,1,1]
	v_pk_fma_f32 v[78:79], v[182:183], v[80:81], v[78:79] op_sel_hi:[0,1,1]
	v_pk_fma_f32 v[100:101], v[184:185], v[80:81], v[88:89] op_sel_hi:[0,1,1]
	v_pk_fma_f32 v[68:69], v[186:187], v[80:81], v[68:69] op_sel_hi:[0,1,1]
	v_pk_fma_f32 v[44:45], v[180:181], v[56:57], v[44:45] op_sel_hi:[0,1,1]
	v_pk_fma_f32 v[50:51], v[182:183], v[56:57], v[50:51] op_sel_hi:[0,1,1]
	v_pk_fma_f32 v[54:55], v[184:185], v[56:57], v[54:55] op_sel_hi:[0,1,1]
	v_pk_fma_f32 v[48:49], v[186:187], v[56:57], v[48:49] op_sel_hi:[0,1,1]
	v_mov_b32_dpp v52, v60 quad_perm:[0,0,0,0] row_mask:0xf bank_mask:0xf bound_ctrl:1
	v_mov_b32_dpp v56, v60 quad_perm:[2,2,2,2] row_mask:0xf bank_mask:0xf bound_ctrl:1
	v_mov_b32_dpp v64, v60 quad_perm:[1,1,1,1] row_mask:0xf bank_mask:0xf bound_ctrl:1
	v_mov_b32_dpp v76, v60 quad_perm:[3,3,3,3] row_mask:0xf bank_mask:0xf bound_ctrl:1
	v_add_f32_e32 v165, v60, v167
	v_pk_fma_f32 v[94:95], v[52:53], v[38:39], v[94:95] op_sel_hi:[0,1,1]
	v_pk_fma_f32 v[86:87], v[56:57], v[38:39], v[86:87] op_sel_hi:[0,1,1]
	v_pk_fma_f32 v[98:99], v[64:65], v[38:39], v[98:99] op_sel_hi:[0,1,1]
	v_pk_fma_f32 v[110:111], v[76:77], v[38:39], v[66:67] op_sel_hi:[0,1,1]
	v_pk_fma_f32 v[96:97], v[52:53], v[40:41], v[74:75] op_sel_hi:[0,1,1]
	v_pk_fma_f32 v[88:89], v[56:57], v[40:41], v[78:79] op_sel_hi:[0,1,1]
	v_pk_fma_f32 v[100:101], v[64:65], v[40:41], v[100:101] op_sel_hi:[0,1,1]
	v_pk_fma_f32 v[112:113], v[76:77], v[40:41], v[68:69] op_sel_hi:[0,1,1]
	v_pk_fma_f32 v[42:43], v[52:53], v[34:35], v[42:43] op_sel_hi:[0,1,1]
	v_pk_fma_f32 v[58:59], v[56:57], v[34:35], v[58:59] op_sel_hi:[0,1,1]
	v_pk_fma_f32 v[62:63], v[64:65], v[34:35], v[62:63] op_sel_hi:[0,1,1]
	v_pk_fma_f32 v[82:83], v[76:77], v[34:35], v[46:47] op_sel_hi:[0,1,1]
	v_pk_fma_f32 v[44:45], v[52:53], v[36:37], v[44:45] op_sel_hi:[0,1,1]
	v_pk_fma_f32 v[60:61], v[56:57], v[36:37], v[50:51] op_sel_hi:[0,1,1]
	v_pk_fma_f32 v[64:65], v[64:65], v[36:37], v[54:55] op_sel_hi:[0,1,1]
	v_pk_fma_f32 v[84:85], v[76:77], v[36:37], v[48:49] op_sel_hi:[0,1,1]
	s_branch .LBB0_1130

.LBB0_1130:
	s_cmp_gt_i32 s51, 4
	s_cselect_b64 s[76:77], -1, 0
	s_and_b64 s[82:83], s[76:77], exec
	s_cselect_b32 s81, -5, 27
	s_cselect_b32 s82, s11, s1
	s_and_b64 s[76:77], s[76:77], s[38:39]
	s_add_i32 s81, s81, s51
	s_and_b64 s[76:77], s[76:77], exec
	s_cselect_b32 s84, s63, s61
	s_cselect_b32 s85, s62, s60
	s_ashr_i32 s83, s82, 31
	s_lshl_b64 s[76:77], s[82:83], 18
	s_add_u32 s76, s85, s76
	s_addc_u32 s77, s84, s77
	s_lshl_b64 s[82:83], s[82:83], 12
	s_add_u32 s82, s64, s82
	s_addc_u32 s83, s65, s83
	v_lshl_or_b32 v164, s81, 7, v239
	global_load_dword v246, v164, s[82:83] offset:0
	v_lshl_or_b32 v34, s81, 13, v243
	global_load_dwordx4 v[66:69], v34, s[76:77] offset:2048 sc1 nt
	global_load_dwordx4 v[46:49], v34, s[76:77] offset:2176 sc1 nt
	global_load_dwordx4 v[74:77], v34, s[76:77] offset:0 sc1 nt
	global_load_dwordx4 v[50:53], v34, s[76:77] offset:128 sc1 nt
	global_load_dwordx4 v[78:81], v34, s[76:77] offset:-2048 sc1 nt
	global_load_dwordx4 v[54:57], v34, s[76:77] offset:-1920 sc1 nt
	global_load_dwordx4 v[38:41], v34, s[76:77] offset:-4096 sc1 nt
	global_load_dwordx4 v[34:37], v34, s[76:77] offset:-3968 sc1 nt
	s_waitcnt vmcnt(33)
	s_mov_b64 s[76:77], -1
	s_and_b64 vcc, exec, s[74:75]
	s_cbranch_vccz .LBB0_1134
	v_pk_mul_f32 v[166:167], v[122:123], v[94:95]
	v_pk_mul_f32 v[168:169], v[122:123], v[86:87]
	v_pk_mul_f32 v[170:171], v[122:123], v[98:99]
	v_pk_mul_f32 v[172:173], v[122:123], v[110:111]
	v_pk_fma_f32 v[166:167], v[96:97], v[124:125], v[166:167]
	v_pk_fma_f32 v[168:169], v[88:89], v[124:125], v[168:169]
	v_pk_fma_f32 v[170:171], v[100:101], v[124:125], v[170:171]
	v_pk_fma_f32 v[172:173], v[112:113], v[124:125], v[172:173]
	v_pk_fma_f32 v[166:167], v[42:43], v[114:115], v[166:167]
	v_pk_fma_f32 v[168:169], v[58:59], v[114:115], v[168:169]
	v_pk_fma_f32 v[170:171], v[62:63], v[114:115], v[170:171]
	v_pk_fma_f32 v[172:173], v[82:83], v[114:115], v[172:173]
	v_pk_fma_f32 v[166:167], v[44:45], v[116:117], v[166:167]
	v_pk_fma_f32 v[168:169], v[60:61], v[116:117], v[168:169]
	v_pk_fma_f32 v[170:171], v[64:65], v[116:117], v[170:171]
	v_pk_fma_f32 v[172:173], v[84:85], v[116:117], v[172:173]
	v_pk_add_f32 v[166:167], v[166:167], v[166:167] op_sel:[0,1] op_sel_hi:[1,0]
	v_pk_add_f32 v[168:169], v[168:169], v[168:169] op_sel:[0,1] op_sel_hi:[1,0]
	v_pk_add_f32 v[170:171], v[170:171], v[170:171] op_sel:[0,1] op_sel_hi:[1,0]
	v_pk_add_f32 v[172:173], v[172:173], v[172:173] op_sel:[0,1] op_sel_hi:[1,0]
	v_cndmask_b32_e64 v164, v166, v170, s[4:5]
	v_cndmask_b32_e64 v167, v168, v172, s[4:5]
	v_cndmask_b32_e64 v166, v170, v166, s[4:5]
	v_cndmask_b32_e64 v168, v172, v168, s[4:5]
	s_waitcnt vmcnt(31)
	v_pk_mul_f32 v[170:171], v[126:127], v[98:99]
	v_add_f32_dpp v164, v164, v166 quad_perm:[1,0,3,2] row_mask:0xf bank_mask:0xf bound_ctrl:1
	v_add_f32_dpp v166, v167, v168 quad_perm:[1,0,3,2] row_mask:0xf bank_mask:0xf bound_ctrl:1
	v_cndmask_b32_e64 v167, v164, v166, s[6:7]
	v_cndmask_b32_e64 v164, v166, v164, s[6:7]
	v_pk_mul_f32 v[168:169], v[126:127], v[86:87]
	v_pk_mul_f32 v[172:173], v[126:127], v[110:111]
	v_add_f32_dpp v175, v167, v164 quad_perm:[2,3,0,1] row_mask:0xf bank_mask:0xf bound_ctrl:1
	v_pk_mul_f32 v[166:167], v[126:127], v[94:95]
	v_pk_fma_f32 v[168:169], v[88:89], v[128:129], v[168:169]
	v_pk_fma_f32 v[166:167], v[96:97], v[128:129], v[166:167]
	v_pk_fma_f32 v[170:171], v[100:101], v[128:129], v[170:171]
	v_pk_fma_f32 v[172:173], v[112:113], v[128:129], v[172:173]
	v_pk_fma_f32 v[166:167], v[42:43], v[118:119], v[166:167]
	v_pk_fma_f32 v[168:169], v[58:59], v[118:119], v[168:169]
	v_pk_fma_f32 v[170:171], v[62:63], v[118:119], v[170:171]
	v_pk_fma_f32 v[172:173], v[82:83], v[118:119], v[172:173]
	v_pk_fma_f32 v[166:167], v[44:45], v[120:121], v[166:167]
	v_pk_fma_f32 v[168:169], v[60:61], v[120:121], v[168:169]
	v_pk_fma_f32 v[170:171], v[64:65], v[120:121], v[170:171]
	v_pk_fma_f32 v[172:173], v[84:85], v[120:121], v[172:173]
	v_pk_add_f32 v[166:167], v[166:167], v[166:167] op_sel:[0,1] op_sel_hi:[1,0]
	v_pk_add_f32 v[168:169], v[168:169], v[168:169] op_sel:[0,1] op_sel_hi:[1,0]
	v_pk_add_f32 v[170:171], v[170:171], v[170:171] op_sel:[0,1] op_sel_hi:[1,0]
	v_pk_add_f32 v[172:173], v[172:173], v[172:173] op_sel:[0,1] op_sel_hi:[1,0]
	v_cndmask_b32_e64 v164, v166, v170, s[4:5]
	v_cndmask_b32_e64 v167, v168, v172, s[4:5]
	v_cndmask_b32_e64 v166, v170, v166, s[4:5]
	v_cndmask_b32_e64 v168, v172, v168, s[4:5]
	ds_swizzle_b32 v178, v175 offset:swizzle(SWAP,4)
	v_add_f32_dpp v164, v164, v166 quad_perm:[1,0,3,2] row_mask:0xf bank_mask:0xf bound_ctrl:1
	v_add_f32_dpp v166, v167, v168 quad_perm:[1,0,3,2] row_mask:0xf bank_mask:0xf bound_ctrl:1
	v_cndmask_b32_e64 v167, v164, v166, s[6:7]
	v_cndmask_b32_e64 v164, v166, v164, s[6:7]
	v_mov_b32_dpp v174, v238 quad_perm:[0,0,0,0] row_mask:0xf bank_mask:0xf bound_ctrl:1
	s_waitcnt lgkmcnt(0)
	v_add_f32_e32 v166, v175, v178
	v_add_f32_dpp v167, v167, v164 quad_perm:[2,3,0,1] row_mask:0xf bank_mask:0xf bound_ctrl:1
	ds_swizzle_b32 v168, v167 offset:swizzle(SWAP,4)
	v_add_f32_e32 v178, v165, v174
	s_waitcnt vmcnt(29)
	v_pk_mul_f32 v[170:171], v[106:107], v[86:87]
	v_pk_mul_f32 v[172:173], v[106:107], v[98:99]
	v_pk_mul_f32 v[174:175], v[106:107], v[110:111]
	s_waitcnt lgkmcnt(0)
	v_add_f32_e32 v167, v167, v168
	v_pk_mul_f32 v[168:169], v[106:107], v[94:95]
	v_pk_fma_f32 v[170:171], v[88:89], v[108:109], v[170:171]
	v_pk_fma_f32 v[168:169], v[96:97], v[108:109], v[168:169]
	v_pk_fma_f32 v[172:173], v[100:101], v[108:109], v[172:173]
	v_pk_fma_f32 v[174:175], v[112:113], v[108:109], v[174:175]
	v_pk_fma_f32 v[168:169], v[42:43], v[102:103], v[168:169]
	v_pk_fma_f32 v[170:171], v[58:59], v[102:103], v[170:171]
	v_pk_fma_f32 v[172:173], v[62:63], v[102:103], v[172:173]
	v_pk_fma_f32 v[174:175], v[82:83], v[102:103], v[174:175]
	v_pk_fma_f32 v[168:169], v[44:45], v[104:105], v[168:169]
	v_pk_fma_f32 v[170:171], v[60:61], v[104:105], v[170:171]
	v_pk_fma_f32 v[172:173], v[64:65], v[104:105], v[172:173]
	v_pk_fma_f32 v[174:175], v[84:85], v[104:105], v[174:175]
	v_pk_add_f32 v[168:169], v[168:169], v[168:169] op_sel:[0,1] op_sel_hi:[1,0]
	v_pk_add_f32 v[170:171], v[170:171], v[170:171] op_sel:[0,1] op_sel_hi:[1,0]
	v_pk_add_f32 v[172:173], v[172:173], v[172:173] op_sel:[0,1] op_sel_hi:[1,0]
	v_pk_add_f32 v[174:175], v[174:175], v[174:175] op_sel:[0,1] op_sel_hi:[1,0]
	v_cndmask_b32_e64 v169, v168, v172, s[4:5]
	v_cndmask_b32_e64 v171, v170, v174, s[4:5]
	v_cndmask_b32_e64 v168, v172, v168, s[4:5]
	v_cndmask_b32_e64 v170, v174, v170, s[4:5]
	s_waitcnt vmcnt(27)
	v_pk_mul_f32 v[172:173], v[90:91], v[98:99]
	v_add_f32_dpp v168, v169, v168 quad_perm:[1,0,3,2] row_mask:0xf bank_mask:0xf bound_ctrl:1
	v_add_f32_dpp v169, v171, v170 quad_perm:[1,0,3,2] row_mask:0xf bank_mask:0xf bound_ctrl:1
	v_cndmask_b32_e64 v170, v168, v169, s[6:7]
	v_cndmask_b32_e64 v168, v169, v168, s[6:7]
	v_pk_mul_f32 v[174:175], v[90:91], v[110:111]
	v_pk_fma_f32 v[172:173], v[100:101], v[92:93], v[172:173]
	v_add_f32_dpp v179, v170, v168 quad_perm:[2,3,0,1] row_mask:0xf bank_mask:0xf bound_ctrl:1
	v_pk_mul_f32 v[168:169], v[90:91], v[94:95]
	v_pk_mul_f32 v[170:171], v[90:91], v[86:87]
	v_pk_fma_f32 v[168:169], v[96:97], v[92:93], v[168:169]
	v_pk_fma_f32 v[170:171], v[88:89], v[92:93], v[170:171]
	v_pk_fma_f32 v[174:175], v[112:113], v[92:93], v[174:175]
	v_pk_fma_f32 v[168:169], v[42:43], v[70:71], v[168:169]
	v_pk_fma_f32 v[170:171], v[58:59], v[70:71], v[170:171]
	v_pk_fma_f32 v[172:173], v[62:63], v[70:71], v[172:173]
	v_pk_fma_f32 v[174:175], v[82:83], v[70:71], v[174:175]
	v_pk_fma_f32 v[168:169], v[44:45], v[72:73], v[168:169]
	v_pk_fma_f32 v[170:171], v[60:61], v[72:73], v[170:171]
	v_pk_fma_f32 v[172:173], v[64:65], v[72:73], v[172:173]
	v_pk_fma_f32 v[174:175], v[84:85], v[72:73], v[174:175]
	v_pk_add_f32 v[168:169], v[168:169], v[168:169] op_sel:[0,1] op_sel_hi:[1,0]
	v_pk_add_f32 v[170:171], v[170:171], v[170:171] op_sel:[0,1] op_sel_hi:[1,0]
	v_pk_add_f32 v[172:173], v[172:173], v[172:173] op_sel:[0,1] op_sel_hi:[1,0]
	v_pk_add_f32 v[174:175], v[174:175], v[174:175] op_sel:[0,1] op_sel_hi:[1,0]
	v_cndmask_b32_e64 v169, v168, v172, s[4:5]
	v_cndmask_b32_e64 v171, v170, v174, s[4:5]
	v_cndmask_b32_e64 v168, v172, v168, s[4:5]
	v_cndmask_b32_e64 v170, v174, v170, s[4:5]
	ds_swizzle_b32 v180, v179 offset:swizzle(SWAP,4)
	v_add_f32_dpp v168, v169, v168 quad_perm:[1,0,3,2] row_mask:0xf bank_mask:0xf bound_ctrl:1
	v_add_f32_dpp v169, v171, v170 quad_perm:[1,0,3,2] row_mask:0xf bank_mask:0xf bound_ctrl:1
	v_cndmask_b32_e64 v170, v168, v169, s[6:7]
	v_cndmask_b32_e64 v168, v169, v168, s[6:7]
	v_mov_b32_dpp v176, v238 quad_perm:[1,1,1,1] row_mask:0xf bank_mask:0xf bound_ctrl:1
	v_mov_b32_dpp v177, v238 quad_perm:[2,2,2,2] row_mask:0xf bank_mask:0xf bound_ctrl:1
	v_add_f32_dpp v169, v170, v168 quad_perm:[2,3,0,1] row_mask:0xf bank_mask:0xf bound_ctrl:1
	ds_swizzle_b32 v171, v169 offset:swizzle(SWAP,4)
	v_add_f32_e32 v170, v178, v176
	s_waitcnt lgkmcnt(1)
	v_add_f32_e32 v168, v179, v180
	v_fmac_f32_e32 v168, 0x3fb8aa3b, v170
	v_add_f32_e32 v170, v170, v177
	s_waitcnt lgkmcnt(0)
	v_add_f32_e32 v169, v169, v171
	v_mov_b32_dpp v164, v238 quad_perm:[3,3,3,3] row_mask:0xf bank_mask:0xf bound_ctrl:1
	v_fmac_f32_e32 v166, 0x3fb8aa3b, v165
	v_fmac_f32_e32 v167, 0x3fb8aa3b, v178
	v_fmac_f32_e32 v169, 0x3fb8aa3b, v170
	s_and_saveexec_b64 s[76:77], s[8:9]
	s_cbranch_execz .LBB0_1133
	v_add_u32_e32 v173, 0xfffffd80, v163
	v_add_u32_e32 v171, 0xfffffc80, v163
	v_add_u32_e32 v172, 0xfffffd00, v163
	v_add_u32_e32 v174, 0xfffffc00, v163
	ds_write_b32 v173, v166
	ds_write_b32 v172, v167
	ds_write_b32 v171, v168
	ds_write_b32 v174, v169

.LBB0_1134:
	s_andn2_b64 vcc, exec, s[76:77]
	s_cbranch_vccnz .LBB0_1136
	s_waitcnt vmcnt(27)
	v_add_u32_e32 v166, 0xfffffd80, v163
	ds_read_b32 v166, v166
	v_add_u32_e32 v164, 0xfffffc00, v163
	v_add_u32_e32 v167, 0xfffffd00, v163
	v_add_u32_e32 v163, 0xfffffc80, v163
	ds_read_b32 v167, v167
	ds_read_b32 v163, v163
	ds_read_b32 v169, v164
	s_waitcnt lgkmcnt(3)
	v_sub_f32_e32 v164, v166, v248
	v_exp_f32_e32 v170, v164
	s_waitcnt lgkmcnt(2)
	v_sub_f32_e32 v166, v167, v248
	v_exp_f32_e32 v167, v166
	v_add_f32_e32 v165, v165, v170
	v_mov_b32_dpp v164, v170 quad_perm:[0,0,0,0] row_mask:0xf bank_mask:0xf bound_ctrl:1
	v_mov_b32_dpp v166, v170 quad_perm:[2,2,2,2] row_mask:0xf bank_mask:0xf bound_ctrl:1
	v_mov_b32_dpp v168, v170 quad_perm:[1,1,1,1] row_mask:0xf bank_mask:0xf bound_ctrl:1
	v_mov_b32_dpp v170, v170 quad_perm:[3,3,3,3] row_mask:0xf bank_mask:0xf bound_ctrl:1
	v_add_f32_e32 v165, v167, v165
	v_pk_fma_f32 v[42:43], v[164:165], v[114:115], v[42:43] op_sel_hi:[0,1,1]
	v_pk_fma_f32 v[58:59], v[166:167], v[114:115], v[58:59] op_sel_hi:[0,1,1]
	s_waitcnt lgkmcnt(0)
	v_pk_fma_f32 v[62:63], v[168:169], v[114:115], v[62:63] op_sel_hi:[0,1,1]
	v_pk_fma_f32 v[82:83], v[170:171], v[114:115], v[82:83] op_sel_hi:[0,1,1]
	v_sub_f32_e32 v114, v163, v248
	v_exp_f32_e32 v115, v114
	v_mov_b32_dpp v172, v167 quad_perm:[0,0,0,0] row_mask:0xf bank_mask:0xf bound_ctrl:1
	v_mov_b32_dpp v174, v167 quad_perm:[2,2,2,2] row_mask:0xf bank_mask:0xf bound_ctrl:1
	v_mov_b32_dpp v176, v167 quad_perm:[1,1,1,1] row_mask:0xf bank_mask:0xf bound_ctrl:1
	v_mov_b32_dpp v178, v167 quad_perm:[3,3,3,3] row_mask:0xf bank_mask:0xf bound_ctrl:1
	v_pk_fma_f32 v[44:45], v[164:165], v[116:117], v[44:45] op_sel_hi:[0,1,1]
	v_pk_fma_f32 v[60:61], v[166:167], v[116:117], v[60:61] op_sel_hi:[0,1,1]
	v_pk_fma_f32 v[64:65], v[168:169], v[116:117], v[64:65] op_sel_hi:[0,1,1]
	v_pk_fma_f32 v[84:85], v[170:171], v[116:117], v[84:85] op_sel_hi:[0,1,1]
	v_pk_fma_f32 v[42:43], v[172:173], v[118:119], v[42:43] op_sel_hi:[0,1,1]
	v_pk_fma_f32 v[58:59], v[174:175], v[118:119], v[58:59] op_sel_hi:[0,1,1]
	v_pk_fma_f32 v[62:63], v[176:177], v[118:119], v[62:63] op_sel_hi:[0,1,1]
	v_pk_fma_f32 v[82:83], v[178:179], v[118:119], v[82:83] op_sel_hi:[0,1,1]
	v_pk_fma_f32 v[44:45], v[172:173], v[120:121], v[44:45] op_sel_hi:[0,1,1]
	v_pk_fma_f32 v[60:61], v[174:175], v[120:121], v[60:61] op_sel_hi:[0,1,1]
	v_pk_fma_f32 v[64:65], v[176:177], v[120:121], v[64:65] op_sel_hi:[0,1,1]
	v_pk_fma_f32 v[84:85], v[178:179], v[120:121], v[84:85] op_sel_hi:[0,1,1]
	v_add_f32_e32 v117, v115, v165
	v_mov_b32_dpp v114, v115 quad_perm:[0,0,0,0] row_mask:0xf bank_mask:0xf bound_ctrl:1
	v_mov_b32_dpp v116, v115 quad_perm:[2,2,2,2] row_mask:0xf bank_mask:0xf bound_ctrl:1
	v_mov_b32_dpp v118, v115 quad_perm:[1,1,1,1] row_mask:0xf bank_mask:0xf bound_ctrl:1
	v_mov_b32_dpp v120, v115 quad_perm:[3,3,3,3] row_mask:0xf bank_mask:0xf bound_ctrl:1
	v_pk_fma_f32 v[42:43], v[114:115], v[102:103], v[42:43] op_sel_hi:[0,1,1]
	v_pk_fma_f32 v[58:59], v[116:117], v[102:103], v[58:59] op_sel_hi:[0,1,1]
	v_pk_fma_f32 v[62:63], v[118:119], v[102:103], v[62:63] op_sel_hi:[0,1,1]
	v_pk_fma_f32 v[82:83], v[120:121], v[102:103], v[82:83] op_sel_hi:[0,1,1]
	v_sub_f32_e32 v102, v169, v248
	v_exp_f32_e32 v103, v102
	v_pk_fma_f32 v[94:95], v[164:165], v[122:123], v[94:95] op_sel_hi:[0,1,1]
	v_pk_fma_f32 v[86:87], v[166:167], v[122:123], v[86:87] op_sel_hi:[0,1,1]
	v_pk_fma_f32 v[98:99], v[168:169], v[122:123], v[98:99] op_sel_hi:[0,1,1]
	v_pk_fma_f32 v[110:111], v[170:171], v[122:123], v[110:111] op_sel_hi:[0,1,1]
	v_pk_fma_f32 v[96:97], v[164:165], v[124:125], v[96:97] op_sel_hi:[0,1,1]
	v_pk_fma_f32 v[88:89], v[166:167], v[124:125], v[88:89] op_sel_hi:[0,1,1]
	v_pk_fma_f32 v[100:101], v[168:169], v[124:125], v[100:101] op_sel_hi:[0,1,1]
	v_pk_fma_f32 v[112:113], v[170:171], v[124:125], v[112:113] op_sel_hi:[0,1,1]
	v_pk_fma_f32 v[94:95], v[172:173], v[126:127], v[94:95] op_sel_hi:[0,1,1]
	v_pk_fma_f32 v[86:87], v[174:175], v[126:127], v[86:87] op_sel_hi:[0,1,1]
	v_pk_fma_f32 v[98:99], v[176:177], v[126:127], v[98:99] op_sel_hi:[0,1,1]
	v_pk_fma_f32 v[110:111], v[178:179], v[126:127], v[110:111] op_sel_hi:[0,1,1]
	v_pk_fma_f32 v[96:97], v[172:173], v[128:129], v[96:97] op_sel_hi:[0,1,1]
	v_pk_fma_f32 v[88:89], v[174:175], v[128:129], v[88:89] op_sel_hi:[0,1,1]
	v_pk_fma_f32 v[100:101], v[176:177], v[128:129], v[100:101] op_sel_hi:[0,1,1]
	v_pk_fma_f32 v[112:113], v[178:179], v[128:129], v[112:113] op_sel_hi:[0,1,1]
	v_pk_fma_f32 v[94:95], v[114:115], v[106:107], v[94:95] op_sel_hi:[0,1,1]
	v_pk_fma_f32 v[86:87], v[116:117], v[106:107], v[86:87] op_sel_hi:[0,1,1]
	v_pk_fma_f32 v[98:99], v[118:119], v[106:107], v[98:99] op_sel_hi:[0,1,1]
	v_pk_fma_f32 v[106:107], v[120:121], v[106:107], v[110:111] op_sel_hi:[0,1,1]
	v_pk_fma_f32 v[96:97], v[114:115], v[108:109], v[96:97] op_sel_hi:[0,1,1]
	v_pk_fma_f32 v[88:89], v[116:117], v[108:109], v[88:89] op_sel_hi:[0,1,1]
	v_pk_fma_f32 v[100:101], v[118:119], v[108:109], v[100:101] op_sel_hi:[0,1,1]
	v_pk_fma_f32 v[108:109], v[120:121], v[108:109], v[112:113] op_sel_hi:[0,1,1]
	v_pk_fma_f32 v[44:45], v[114:115], v[104:105], v[44:45] op_sel_hi:[0,1,1]
	v_pk_fma_f32 v[60:61], v[116:117], v[104:105], v[60:61] op_sel_hi:[0,1,1]
	v_pk_fma_f32 v[64:65], v[118:119], v[104:105], v[64:65] op_sel_hi:[0,1,1]
	v_pk_fma_f32 v[84:85], v[120:121], v[104:105], v[84:85] op_sel_hi:[0,1,1]
	v_mov_b32_dpp v102, v103 quad_perm:[0,0,0,0] row_mask:0xf bank_mask:0xf bound_ctrl:1
	v_mov_b32_dpp v104, v103 quad_perm:[2,2,2,2] row_mask:0xf bank_mask:0xf bound_ctrl:1
	v_mov_b32_dpp v114, v103 quad_perm:[1,1,1,1] row_mask:0xf bank_mask:0xf bound_ctrl:1
	v_mov_b32_dpp v116, v103 quad_perm:[3,3,3,3] row_mask:0xf bank_mask:0xf bound_ctrl:1
	v_add_f32_e32 v164, v103, v117
	v_pk_fma_f32 v[94:95], v[102:103], v[90:91], v[94:95] op_sel_hi:[0,1,1]
	v_pk_fma_f32 v[86:87], v[104:105], v[90:91], v[86:87] op_sel_hi:[0,1,1]
	v_pk_fma_f32 v[98:99], v[114:115], v[90:91], v[98:99] op_sel_hi:[0,1,1]
	v_pk_fma_f32 v[110:111], v[116:117], v[90:91], v[106:107] op_sel_hi:[0,1,1]
	v_pk_fma_f32 v[96:97], v[102:103], v[92:93], v[96:97] op_sel_hi:[0,1,1]
	v_pk_fma_f32 v[88:89], v[104:105], v[92:93], v[88:89] op_sel_hi:[0,1,1]
	v_pk_fma_f32 v[100:101], v[114:115], v[92:93], v[100:101] op_sel_hi:[0,1,1]
	v_pk_fma_f32 v[112:113], v[116:117], v[92:93], v[108:109] op_sel_hi:[0,1,1]
	v_pk_fma_f32 v[42:43], v[102:103], v[70:71], v[42:43] op_sel_hi:[0,1,1]
	v_pk_fma_f32 v[58:59], v[104:105], v[70:71], v[58:59] op_sel_hi:[0,1,1]
	v_pk_fma_f32 v[62:63], v[114:115], v[70:71], v[62:63] op_sel_hi:[0,1,1]
	v_pk_fma_f32 v[82:83], v[116:117], v[70:71], v[82:83] op_sel_hi:[0,1,1]
	v_pk_fma_f32 v[44:45], v[102:103], v[72:73], v[44:45] op_sel_hi:[0,1,1]
	v_pk_fma_f32 v[60:61], v[104:105], v[72:73], v[60:61] op_sel_hi:[0,1,1]
	v_pk_fma_f32 v[64:65], v[114:115], v[72:73], v[64:65] op_sel_hi:[0,1,1]
	v_pk_fma_f32 v[84:85], v[116:117], v[72:73], v[84:85] op_sel_hi:[0,1,1]
	s_branch .LBB0_1137

.LBB0_1137:
	s_cmp_gt_i32 s51, 5
	s_cselect_b64 s[76:77], -1, 0
	s_and_b64 s[82:83], s[76:77], exec
	s_cselect_b32 s81, -6, 26
	s_cselect_b32 s82, s11, s1
	s_and_b64 s[76:77], s[76:77], s[38:39]
	s_add_i32 s81, s81, s51
	s_and_b64 s[76:77], s[76:77], exec
	s_cselect_b32 s84, s63, s61
	s_cselect_b32 s85, s62, s60
	s_ashr_i32 s83, s82, 31
	s_lshl_b64 s[76:77], s[82:83], 18
	s_add_u32 s76, s85, s76
	s_addc_u32 s77, s84, s77
	s_lshl_b64 s[82:83], s[82:83], 12
	s_add_u32 s82, s64, s82
	s_addc_u32 s83, s65, s83
	v_lshl_or_b32 v163, s81, 7, v239
	global_load_dword v238, v163, s[82:83] offset:0
	v_lshl_or_b32 v70, s81, 13, v243
	global_load_dwordx4 v[122:125], v70, s[76:77] offset:2048 sc1 nt
	global_load_dwordx4 v[114:117], v70, s[76:77] offset:2176 sc1 nt
	global_load_dwordx4 v[126:129], v70, s[76:77] offset:0 sc1 nt
	global_load_dwordx4 v[118:121], v70, s[76:77] offset:128 sc1 nt
	global_load_dwordx4 v[106:109], v70, s[76:77] offset:-2048 sc1 nt
	global_load_dwordx4 v[102:105], v70, s[76:77] offset:-1920 sc1 nt
	global_load_dwordx4 v[90:93], v70, s[76:77] offset:-4096 sc1 nt
	global_load_dwordx4 v[70:73], v70, s[76:77] offset:-3968 sc1 nt
	s_waitcnt vmcnt(33)
	s_mov_b64 s[76:77], -1
	s_and_b64 vcc, exec, s[74:75]
	s_cbranch_vccz .LBB0_1141
	v_pk_mul_f32 v[166:167], v[150:151], v[94:95]
	v_pk_mul_f32 v[168:169], v[150:151], v[86:87]
	v_pk_mul_f32 v[170:171], v[150:151], v[98:99]
	v_pk_mul_f32 v[172:173], v[150:151], v[110:111]
	v_pk_fma_f32 v[166:167], v[96:97], v[152:153], v[166:167]
	v_pk_fma_f32 v[168:169], v[88:89], v[152:153], v[168:169]
	v_pk_fma_f32 v[170:171], v[100:101], v[152:153], v[170:171]
	v_pk_fma_f32 v[172:173], v[112:113], v[152:153], v[172:173]
	v_pk_fma_f32 v[166:167], v[42:43], v[138:139], v[166:167]
	v_pk_fma_f32 v[168:169], v[58:59], v[138:139], v[168:169]
	v_pk_fma_f32 v[170:171], v[62:63], v[138:139], v[170:171]
	v_pk_fma_f32 v[172:173], v[82:83], v[138:139], v[172:173]
	v_pk_fma_f32 v[166:167], v[44:45], v[140:141], v[166:167]
	v_pk_fma_f32 v[168:169], v[60:61], v[140:141], v[168:169]
	v_pk_fma_f32 v[170:171], v[64:65], v[140:141], v[170:171]
	v_pk_fma_f32 v[172:173], v[84:85], v[140:141], v[172:173]
	v_pk_add_f32 v[166:167], v[166:167], v[166:167] op_sel:[0,1] op_sel_hi:[1,0]
	v_pk_add_f32 v[168:169], v[168:169], v[168:169] op_sel:[0,1] op_sel_hi:[1,0]
	v_pk_add_f32 v[170:171], v[170:171], v[170:171] op_sel:[0,1] op_sel_hi:[1,0]
	v_pk_add_f32 v[172:173], v[172:173], v[172:173] op_sel:[0,1] op_sel_hi:[1,0]
	v_cndmask_b32_e64 v163, v166, v170, s[4:5]
	v_cndmask_b32_e64 v167, v168, v172, s[4:5]
	v_cndmask_b32_e64 v166, v170, v166, s[4:5]
	v_cndmask_b32_e64 v168, v172, v168, s[4:5]
	s_waitcnt vmcnt(31)
	v_pk_mul_f32 v[170:171], v[154:155], v[98:99]
	v_add_f32_dpp v163, v163, v166 quad_perm:[1,0,3,2] row_mask:0xf bank_mask:0xf bound_ctrl:1
	v_add_f32_dpp v166, v167, v168 quad_perm:[1,0,3,2] row_mask:0xf bank_mask:0xf bound_ctrl:1
	v_cndmask_b32_e64 v167, v163, v166, s[6:7]
	v_cndmask_b32_e64 v163, v166, v163, s[6:7]
	v_pk_mul_f32 v[168:169], v[154:155], v[86:87]
	v_pk_mul_f32 v[172:173], v[154:155], v[110:111]
	v_add_f32_dpp v176, v167, v163 quad_perm:[2,3,0,1] row_mask:0xf bank_mask:0xf bound_ctrl:1
	v_pk_mul_f32 v[166:167], v[154:155], v[94:95]
	v_pk_fma_f32 v[168:169], v[88:89], v[156:157], v[168:169]
	v_pk_fma_f32 v[166:167], v[96:97], v[156:157], v[166:167]
	v_pk_fma_f32 v[170:171], v[100:101], v[156:157], v[170:171]
	v_pk_fma_f32 v[172:173], v[112:113], v[156:157], v[172:173]
	v_pk_fma_f32 v[166:167], v[42:43], v[142:143], v[166:167]
	v_pk_fma_f32 v[168:169], v[58:59], v[142:143], v[168:169]
	v_pk_fma_f32 v[170:171], v[62:63], v[142:143], v[170:171]
	v_pk_fma_f32 v[172:173], v[82:83], v[142:143], v[172:173]
	v_pk_fma_f32 v[166:167], v[44:45], v[144:145], v[166:167]
	v_pk_fma_f32 v[168:169], v[60:61], v[144:145], v[168:169]
	v_pk_fma_f32 v[170:171], v[64:65], v[144:145], v[170:171]
	v_pk_fma_f32 v[172:173], v[84:85], v[144:145], v[172:173]
	v_pk_add_f32 v[166:167], v[166:167], v[166:167] op_sel:[0,1] op_sel_hi:[1,0]
	v_pk_add_f32 v[168:169], v[168:169], v[168:169] op_sel:[0,1] op_sel_hi:[1,0]
	v_pk_add_f32 v[170:171], v[170:171], v[170:171] op_sel:[0,1] op_sel_hi:[1,0]
	v_pk_add_f32 v[172:173], v[172:173], v[172:173] op_sel:[0,1] op_sel_hi:[1,0]
	v_cndmask_b32_e64 v163, v166, v170, s[4:5]
	v_cndmask_b32_e64 v167, v168, v172, s[4:5]
	v_cndmask_b32_e64 v166, v170, v166, s[4:5]
	v_cndmask_b32_e64 v168, v172, v168, s[4:5]
	ds_swizzle_b32 v177, v176 offset:swizzle(SWAP,4)
	v_add_f32_dpp v163, v163, v166 quad_perm:[1,0,3,2] row_mask:0xf bank_mask:0xf bound_ctrl:1
	v_add_f32_dpp v166, v167, v168 quad_perm:[1,0,3,2] row_mask:0xf bank_mask:0xf bound_ctrl:1
	v_cndmask_b32_e64 v167, v163, v166, s[6:7]
	v_cndmask_b32_e64 v163, v166, v163, s[6:7]
	v_mov_b32_dpp v165, v162 quad_perm:[0,0,0,0] row_mask:0xf bank_mask:0xf bound_ctrl:1
	v_mov_b32_dpp v174, v162 quad_perm:[1,1,1,1] row_mask:0xf bank_mask:0xf bound_ctrl:1
	v_add_f32_dpp v166, v167, v163 quad_perm:[2,3,0,1] row_mask:0xf bank_mask:0xf bound_ctrl:1
	ds_swizzle_b32 v167, v166 offset:swizzle(SWAP,4)
	v_mov_b32_dpp v175, v162 quad_perm:[2,2,2,2] row_mask:0xf bank_mask:0xf bound_ctrl:1
	v_mov_b32_dpp v163, v162 quad_perm:[3,3,3,3] row_mask:0xf bank_mask:0xf bound_ctrl:1
	s_waitcnt lgkmcnt(1)
	v_add_f32_e32 v162, v176, v177
	v_add_f32_e32 v176, v164, v165
	s_waitcnt lgkmcnt(0)
	v_add_f32_e32 v165, v166, v167
	s_waitcnt vmcnt(29)
	v_pk_mul_f32 v[166:167], v[158:159], v[94:95]
	v_pk_mul_f32 v[168:169], v[158:159], v[86:87]
	v_pk_mul_f32 v[170:171], v[158:159], v[98:99]
	v_pk_mul_f32 v[172:173], v[158:159], v[110:111]
	v_pk_fma_f32 v[166:167], v[96:97], v[160:161], v[166:167]
	v_pk_fma_f32 v[168:169], v[88:89], v[160:161], v[168:169]
	v_pk_fma_f32 v[170:171], v[100:101], v[160:161], v[170:171]
	v_pk_fma_f32 v[172:173], v[112:113], v[160:161], v[172:173]
	v_pk_fma_f32 v[166:167], v[42:43], v[146:147], v[166:167]
	v_pk_fma_f32 v[168:169], v[58:59], v[146:147], v[168:169]
	v_pk_fma_f32 v[170:171], v[62:63], v[146:147], v[170:171]
	v_pk_fma_f32 v[172:173], v[82:83], v[146:147], v[172:173]
	v_pk_fma_f32 v[166:167], v[44:45], v[148:149], v[166:167]
	v_pk_fma_f32 v[168:169], v[60:61], v[148:149], v[168:169]
	v_pk_fma_f32 v[170:171], v[64:65], v[148:149], v[170:171]
	v_pk_fma_f32 v[172:173], v[84:85], v[148:149], v[172:173]
	v_pk_add_f32 v[166:167], v[166:167], v[166:167] op_sel:[0,1] op_sel_hi:[1,0]
	v_pk_add_f32 v[168:169], v[168:169], v[168:169] op_sel:[0,1] op_sel_hi:[1,0]
	v_pk_add_f32 v[170:171], v[170:171], v[170:171] op_sel:[0,1] op_sel_hi:[1,0]
	v_pk_add_f32 v[172:173], v[172:173], v[172:173] op_sel:[0,1] op_sel_hi:[1,0]
	v_cndmask_b32_e64 v167, v166, v170, s[4:5]
	v_cndmask_b32_e64 v169, v168, v172, s[4:5]
	v_cndmask_b32_e64 v166, v170, v166, s[4:5]
	v_cndmask_b32_e64 v168, v172, v168, s[4:5]
	s_waitcnt vmcnt(27)
	v_pk_mul_f32 v[170:171], v[134:135], v[98:99]
	v_add_f32_dpp v166, v167, v166 quad_perm:[1,0,3,2] row_mask:0xf bank_mask:0xf bound_ctrl:1
	v_add_f32_dpp v167, v169, v168 quad_perm:[1,0,3,2] row_mask:0xf bank_mask:0xf bound_ctrl:1
	v_cndmask_b32_e64 v168, v166, v167, s[6:7]
	v_cndmask_b32_e64 v166, v167, v166, s[6:7]
	v_pk_mul_f32 v[172:173], v[134:135], v[110:111]
	v_pk_fma_f32 v[170:171], v[100:101], v[136:137], v[170:171]
	v_add_f32_dpp v177, v168, v166 quad_perm:[2,3,0,1] row_mask:0xf bank_mask:0xf bound_ctrl:1
	v_pk_mul_f32 v[166:167], v[134:135], v[94:95]
	v_pk_mul_f32 v[168:169], v[134:135], v[86:87]
	v_pk_fma_f32 v[166:167], v[96:97], v[136:137], v[166:167]
	v_pk_fma_f32 v[168:169], v[88:89], v[136:137], v[168:169]
	v_pk_fma_f32 v[172:173], v[112:113], v[136:137], v[172:173]
	v_pk_fma_f32 v[166:167], v[42:43], v[130:131], v[166:167]
	v_pk_fma_f32 v[168:169], v[58:59], v[130:131], v[168:169]
	v_pk_fma_f32 v[170:171], v[62:63], v[130:131], v[170:171]
	v_pk_fma_f32 v[172:173], v[82:83], v[130:131], v[172:173]
	v_pk_fma_f32 v[166:167], v[44:45], v[132:133], v[166:167]
	v_pk_fma_f32 v[168:169], v[60:61], v[132:133], v[168:169]
	v_pk_fma_f32 v[170:171], v[64:65], v[132:133], v[170:171]
	v_pk_fma_f32 v[172:173], v[84:85], v[132:133], v[172:173]
	v_pk_add_f32 v[166:167], v[166:167], v[166:167] op_sel:[0,1] op_sel_hi:[1,0]
	v_pk_add_f32 v[168:169], v[168:169], v[168:169] op_sel:[0,1] op_sel_hi:[1,0]
	v_pk_add_f32 v[170:171], v[170:171], v[170:171] op_sel:[0,1] op_sel_hi:[1,0]
	v_pk_add_f32 v[172:173], v[172:173], v[172:173] op_sel:[0,1] op_sel_hi:[1,0]
	v_cndmask_b32_e64 v167, v166, v170, s[4:5]
	v_cndmask_b32_e64 v169, v168, v172, s[4:5]
	v_cndmask_b32_e64 v166, v170, v166, s[4:5]
	v_cndmask_b32_e64 v168, v172, v168, s[4:5]
	ds_swizzle_b32 v178, v177 offset:swizzle(SWAP,4)
	v_add_f32_dpp v166, v167, v166 quad_perm:[1,0,3,2] row_mask:0xf bank_mask:0xf bound_ctrl:1
	v_add_f32_dpp v167, v169, v168 quad_perm:[1,0,3,2] row_mask:0xf bank_mask:0xf bound_ctrl:1
	v_cndmask_b32_e64 v168, v166, v167, s[6:7]
	v_cndmask_b32_e64 v166, v167, v166, s[6:7]
	v_fmac_f32_e32 v162, 0x3fb8aa3b, v164
	v_fmac_f32_e32 v165, 0x3fb8aa3b, v176
	v_add_f32_dpp v167, v168, v166 quad_perm:[2,3,0,1] row_mask:0xf bank_mask:0xf bound_ctrl:1
	ds_swizzle_b32 v169, v167 offset:swizzle(SWAP,4)
	v_add_f32_e32 v168, v176, v174
	s_waitcnt lgkmcnt(1)
	v_add_f32_e32 v166, v177, v178
	v_fmac_f32_e32 v166, 0x3fb8aa3b, v168
	v_add_f32_e32 v168, v168, v175
	s_waitcnt lgkmcnt(0)
	v_add_f32_e32 v167, v167, v169
	v_fmac_f32_e32 v167, 0x3fb8aa3b, v168
	s_and_saveexec_b64 s[74:75], s[8:9]
	s_cbranch_execz .LBB0_1140
	v_lshl_add_u32 v169, s80, 9, v241
	ds_write2_b32 v169, v165, v162 offset0:64 offset1:96
	ds_write2_b32 v169, v167, v166 offset1:32

.LBB0_1141:
	s_andn2_b64 vcc, exec, s[76:77]
	s_cbranch_vccnz .LBB0_1143
	s_waitcnt vmcnt(27)
	v_lshl_add_u32 v165, s80, 9, v241
	ds_read2_b32 v[162:163], v165 offset0:64 offset1:96
	ds_read2_b32 v[166:167], v165 offset1:32
	v_mov_b32_e32 v250, v248
	s_waitcnt lgkmcnt(1)
	v_sub_f32_e32 v163, v163, v248
	v_exp_f32_e32 v163, v163
	v_sub_f32_e32 v162, v162, v248
	v_exp_f32_e32 v165, v162
	s_waitcnt lgkmcnt(0)
	v_sub_f32_e32 v167, v167, v248
	v_exp_f32_e32 v167, v167
	v_add_f32_e32 v169, v164, v163
	v_mov_b32_dpp v162, v163 quad_perm:[0,0,0,0] row_mask:0xf bank_mask:0xf bound_ctrl:1
	v_mov_b32_dpp v164, v163 quad_perm:[2,2,2,2] row_mask:0xf bank_mask:0xf bound_ctrl:1
	v_mov_b32_dpp v168, v163 quad_perm:[1,1,1,1] row_mask:0xf bank_mask:0xf bound_ctrl:1
	v_mov_b32_dpp v170, v163 quad_perm:[3,3,3,3] row_mask:0xf bank_mask:0xf bound_ctrl:1
	v_add_f32_e32 v163, v165, v169
	v_add_f32_e32 v163, v167, v163
	v_pk_fma_f32 v[42:43], v[162:163], v[138:139], v[42:43] op_sel_hi:[0,1,1]
	v_pk_fma_f32 v[58:59], v[164:165], v[138:139], v[58:59] op_sel_hi:[0,1,1]
	v_pk_fma_f32 v[62:63], v[168:169], v[138:139], v[62:63] op_sel_hi:[0,1,1]
	v_pk_fma_f32 v[82:83], v[170:171], v[138:139], v[82:83] op_sel_hi:[0,1,1]
	v_sub_f32_e32 v138, v166, v248
	v_exp_f32_e32 v139, v138
	v_mov_b32_dpp v172, v165 quad_perm:[0,0,0,0] row_mask:0xf bank_mask:0xf bound_ctrl:1
	v_mov_b32_dpp v174, v165 quad_perm:[2,2,2,2] row_mask:0xf bank_mask:0xf bound_ctrl:1
	v_mov_b32_dpp v176, v165 quad_perm:[1,1,1,1] row_mask:0xf bank_mask:0xf bound_ctrl:1
	v_mov_b32_dpp v178, v165 quad_perm:[3,3,3,3] row_mask:0xf bank_mask:0xf bound_ctrl:1
	v_pk_fma_f32 v[94:95], v[162:163], v[150:151], v[94:95] op_sel_hi:[0,1,1]
	v_pk_fma_f32 v[86:87], v[164:165], v[150:151], v[86:87] op_sel_hi:[0,1,1]
	v_pk_fma_f32 v[98:99], v[168:169], v[150:151], v[98:99] op_sel_hi:[0,1,1]
	v_pk_fma_f32 v[110:111], v[170:171], v[150:151], v[110:111] op_sel_hi:[0,1,1]
	v_pk_fma_f32 v[96:97], v[162:163], v[152:153], v[96:97] op_sel_hi:[0,1,1]
	v_pk_fma_f32 v[88:89], v[164:165], v[152:153], v[88:89] op_sel_hi:[0,1,1]
	v_pk_fma_f32 v[100:101], v[168:169], v[152:153], v[100:101] op_sel_hi:[0,1,1]
	v_pk_fma_f32 v[112:113], v[170:171], v[152:153], v[112:113] op_sel_hi:[0,1,1]
	v_pk_fma_f32 v[44:45], v[162:163], v[140:141], v[44:45] op_sel_hi:[0,1,1]
	v_pk_fma_f32 v[60:61], v[164:165], v[140:141], v[60:61] op_sel_hi:[0,1,1]
	v_pk_fma_f32 v[64:65], v[168:169], v[140:141], v[64:65] op_sel_hi:[0,1,1]
	v_pk_fma_f32 v[84:85], v[170:171], v[140:141], v[84:85] op_sel_hi:[0,1,1]
	v_mov_b32_dpp v180, v167 quad_perm:[0,0,0,0] row_mask:0xf bank_mask:0xf bound_ctrl:1
	v_mov_b32_dpp v182, v167 quad_perm:[2,2,2,2] row_mask:0xf bank_mask:0xf bound_ctrl:1
	v_mov_b32_dpp v184, v167 quad_perm:[1,1,1,1] row_mask:0xf bank_mask:0xf bound_ctrl:1
	v_mov_b32_dpp v186, v167 quad_perm:[3,3,3,3] row_mask:0xf bank_mask:0xf bound_ctrl:1
	v_pk_fma_f32 v[94:95], v[172:173], v[154:155], v[94:95] op_sel_hi:[0,1,1]
	v_pk_fma_f32 v[86:87], v[174:175], v[154:155], v[86:87] op_sel_hi:[0,1,1]
	v_pk_fma_f32 v[98:99], v[176:177], v[154:155], v[98:99] op_sel_hi:[0,1,1]
	v_pk_fma_f32 v[110:111], v[178:179], v[154:155], v[110:111] op_sel_hi:[0,1,1]
	v_pk_fma_f32 v[96:97], v[172:173], v[156:157], v[96:97] op_sel_hi:[0,1,1]
	v_pk_fma_f32 v[88:89], v[174:175], v[156:157], v[88:89] op_sel_hi:[0,1,1]
	v_pk_fma_f32 v[100:101], v[176:177], v[156:157], v[100:101] op_sel_hi:[0,1,1]
	v_pk_fma_f32 v[112:113], v[178:179], v[156:157], v[112:113] op_sel_hi:[0,1,1]
	v_pk_fma_f32 v[42:43], v[172:173], v[142:143], v[42:43] op_sel_hi:[0,1,1]
	v_pk_fma_f32 v[58:59], v[174:175], v[142:143], v[58:59] op_sel_hi:[0,1,1]
	v_pk_fma_f32 v[62:63], v[176:177], v[142:143], v[62:63] op_sel_hi:[0,1,1]
	v_pk_fma_f32 v[82:83], v[178:179], v[142:143], v[82:83] op_sel_hi:[0,1,1]
	v_pk_fma_f32 v[44:45], v[172:173], v[144:145], v[44:45] op_sel_hi:[0,1,1]
	v_pk_fma_f32 v[60:61], v[174:175], v[144:145], v[60:61] op_sel_hi:[0,1,1]
	v_pk_fma_f32 v[64:65], v[176:177], v[144:145], v[64:65] op_sel_hi:[0,1,1]
	v_pk_fma_f32 v[84:85], v[178:179], v[144:145], v[84:85] op_sel_hi:[0,1,1]
	v_pk_fma_f32 v[94:95], v[180:181], v[158:159], v[94:95] op_sel_hi:[0,1,1]
	v_pk_fma_f32 v[86:87], v[182:183], v[158:159], v[86:87] op_sel_hi:[0,1,1]
	v_pk_fma_f32 v[98:99], v[184:185], v[158:159], v[98:99] op_sel_hi:[0,1,1]
	v_pk_fma_f32 v[110:111], v[186:187], v[158:159], v[110:111] op_sel_hi:[0,1,1]
	v_pk_fma_f32 v[96:97], v[180:181], v[160:161], v[96:97] op_sel_hi:[0,1,1]
	v_pk_fma_f32 v[88:89], v[182:183], v[160:161], v[88:89] op_sel_hi:[0,1,1]
	v_pk_fma_f32 v[100:101], v[184:185], v[160:161], v[100:101] op_sel_hi:[0,1,1]
	v_pk_fma_f32 v[112:113], v[186:187], v[160:161], v[112:113] op_sel_hi:[0,1,1]
	v_pk_fma_f32 v[42:43], v[180:181], v[146:147], v[42:43] op_sel_hi:[0,1,1]
	v_pk_fma_f32 v[58:59], v[182:183], v[146:147], v[58:59] op_sel_hi:[0,1,1]
	v_pk_fma_f32 v[62:63], v[184:185], v[146:147], v[62:63] op_sel_hi:[0,1,1]
	v_pk_fma_f32 v[82:83], v[186:187], v[146:147], v[82:83] op_sel_hi:[0,1,1]
	v_pk_fma_f32 v[44:45], v[180:181], v[148:149], v[44:45] op_sel_hi:[0,1,1]
	v_pk_fma_f32 v[60:61], v[182:183], v[148:149], v[60:61] op_sel_hi:[0,1,1]
	v_pk_fma_f32 v[64:65], v[184:185], v[148:149], v[64:65] op_sel_hi:[0,1,1]
	v_pk_fma_f32 v[84:85], v[186:187], v[148:149], v[84:85] op_sel_hi:[0,1,1]
	v_add_f32_e32 v251, v139, v163
	v_mov_b32_dpp v138, v139 quad_perm:[0,0,0,0] row_mask:0xf bank_mask:0xf bound_ctrl:1
	v_mov_b32_dpp v140, v139 quad_perm:[2,2,2,2] row_mask:0xf bank_mask:0xf bound_ctrl:1
	v_mov_b32_dpp v142, v139 quad_perm:[1,1,1,1] row_mask:0xf bank_mask:0xf bound_ctrl:1
	v_mov_b32_dpp v144, v139 quad_perm:[3,3,3,3] row_mask:0xf bank_mask:0xf bound_ctrl:1
	v_pk_fma_f32 v[94:95], v[138:139], v[134:135], v[94:95] op_sel_hi:[0,1,1]
	v_pk_fma_f32 v[86:87], v[140:141], v[134:135], v[86:87] op_sel_hi:[0,1,1]
	v_pk_fma_f32 v[98:99], v[142:143], v[134:135], v[98:99] op_sel_hi:[0,1,1]
	v_pk_fma_f32 v[110:111], v[144:145], v[134:135], v[110:111] op_sel_hi:[0,1,1]
	v_pk_fma_f32 v[96:97], v[138:139], v[136:137], v[96:97] op_sel_hi:[0,1,1]
	v_pk_fma_f32 v[88:89], v[140:141], v[136:137], v[88:89] op_sel_hi:[0,1,1]
	v_pk_fma_f32 v[100:101], v[142:143], v[136:137], v[100:101] op_sel_hi:[0,1,1]
	v_pk_fma_f32 v[112:113], v[144:145], v[136:137], v[112:113] op_sel_hi:[0,1,1]
	v_pk_fma_f32 v[42:43], v[138:139], v[130:131], v[42:43] op_sel_hi:[0,1,1]
	v_pk_fma_f32 v[58:59], v[140:141], v[130:131], v[58:59] op_sel_hi:[0,1,1]
	v_pk_fma_f32 v[62:63], v[142:143], v[130:131], v[62:63] op_sel_hi:[0,1,1]
	v_pk_fma_f32 v[82:83], v[144:145], v[130:131], v[82:83] op_sel_hi:[0,1,1]
	v_pk_fma_f32 v[44:45], v[138:139], v[132:133], v[44:45] op_sel_hi:[0,1,1]
	v_pk_fma_f32 v[60:61], v[140:141], v[132:133], v[60:61] op_sel_hi:[0,1,1]
	v_pk_fma_f32 v[64:65], v[142:143], v[132:133], v[64:65] op_sel_hi:[0,1,1]
	v_pk_fma_f32 v[84:85], v[144:145], v[132:133], v[84:85] op_sel_hi:[0,1,1]
	v_mov_b32_e32 v249, v251
	s_cmp_gt_i32 s51, 3
	s_cbranch_scc1 .LBB0_1111
	s_branch .LBB0_1144

.LBB0_1210:
	s_or_b64 exec, exec, s[76:77]
	s_mov_b64 s[76:77], exec
	v_mbcnt_lo_u32_b32 v130, s76, 0
	v_mbcnt_hi_u32_b32 v130, s77, v130
	v_cmp_eq_u32_e32 vcc, 0, v130
	s_waitcnt vmcnt(0)
	buffer_inv sc1
	s_and_saveexec_b64 s[78:79], vcc
	s_cbranch_execz .LBB0_1106
	s_bcnt1_i32_b64 s54, s[76:77]
	v_mov_b32_e32 v130, s54
	global_atomic_add v244, v130, s[74:75] offset:1024
	s_branch .LBB0_1106
	s_nop 0
	s_nop 0
	s_nop 0
	s_nop 0
	s_nop 0
	s_nop 0
	s_nop 0
	s_nop 0
	s_nop 0
	s_nop 0
	s_nop 0
	s_nop 0
	s_nop 0
	s_nop 0
	s_nop 0
	s_nop 0
	s_nop 0
	s_nop 0
	s_nop 0
	s_nop 0
	s_nop 0
	s_nop 0
	s_nop 0
	s_nop 0
	s_nop 0
	s_nop 0
	s_nop 0
	s_nop 0
	s_nop 0
	s_nop 0
	s_nop 0
	s_nop 0
	s_nop 0
	s_nop 0
	s_nop 0
	s_nop 0
	s_nop 0
	s_nop 0
	s_nop 0
	s_nop 0
	s_nop 0
	s_nop 0
	s_nop 0
	s_nop 0
	s_nop 0
	s_nop 0
	s_nop 0
	s_nop 0
